# GEMM tile order: each XCD owns whole 256-row blocks (bit-permuted work-group id) so a consumer GEMM's A rows were produced on its own XCD
# speedup vs baseline: 1.0423x; 1.0423x over previous
;     __device__ bool next(int i, Unit& u) const {
;         const long L = (long)i * G + c; if (L >= nwg) return false;
;         int wgid = (int)L; { const int q = nwg / NXCD, r = nwg % NXCD, xcd = wgid % NXCD, off = wgid / NXCD; wgid = (xcd < r ? xcd * (q + 1) : r * (q + 1) + (xcd - r) * q) + off; }
;         const int nig = WGM * nN, gid = wgid / nig, fm = gid * WGM, gsz = (nM - fm) < WGM ? (nM - fm) : WGM;
;         u.pm = fm + ((wgid % nig) % gsz); u.pn = (wgid % nig) / gsz; return true;
;     }
.LBB0_400:
	s_ashr_i32 s1, s1, 3
	s_add_i32 s1, s8, s1
	s_bfe_u32 s100, s1, 0x10006
	s_bfe_u32 s101, s1, 0x40002
	s_andn2_b32 s1, s1, 0x7c
	s_lshl_b32 s100, s100, 2
	s_lshl_b32 s101, s101, 3
	s_or_b32 s1, s1, s100
	s_or_b32 s1, s1, s101
	s_ashr_i32 s3, s1, 31
	s_lshr_b32 s3, s3, 25
	s_add_i32 s3, s1, s3
	s_ashr_i32 s6, s3, 7
	s_and_b32 s3, s3, 0xff80
	s_sub_i32 s1, s1, s3
	s_bfe_i32 s3, s1, 0x80000
	s_bfe_u32 s3, s3, 0x3000c
	s_add_i32 s3, s1, s3
	s_bfe_i32 s7, s3, 0x80000
	s_and_b32 s3, s3, 0xf8
	s_sub_i32 s1, s1, s3
	s_lshl_b32 s6, s6, 3
	s_sext_i32_i16 s7, s7
	s_sext_i32_i8 s1, s1
	s_add_i32 s8, s6, s1
	s_ashr_i32 s6, s7, 3

;     __device__ bool next(int i, Unit& u) const {
;         const long L = (long)i * G + c; if (L >= nwg) return false;
;         int wgid = (int)L; { const int q = nwg / NXCD, r = nwg % NXCD, xcd = wgid % NXCD, off = wgid / NXCD; wgid = (xcd < r ? xcd * (q + 1) : r * (q + 1) + (xcd - r) * q) + off; }
;         const int nig = WGM * nN, gid = wgid / nig, fm = gid * WGM, gsz = (nM - fm) < WGM ? (nM - fm) : WGM;
;         u.pm = fm + ((wgid % nig) % gsz); u.pn = (wgid % nig) / gsz; return true;
;     }
.LBB0_412:
	s_ashr_i32 s0, s0, 3
	s_add_i32 s0, s3, s0
	s_bfe_u32 s100, s0, 0x10006
	s_bfe_u32 s101, s0, 0x40002
	s_andn2_b32 s0, s0, 0x7c
	s_lshl_b32 s100, s100, 2
	s_lshl_b32 s101, s101, 3
	s_or_b32 s0, s0, s100
	s_or_b32 s0, s0, s101
	s_ashr_i32 s1, s0, 31
	s_lshr_b32 s1, s1, 25
	s_add_i32 s1, s0, s1
	s_ashr_i32 s3, s1, 7
	s_lshl_b32 s3, s3, 3
	s_sub_i32 s7, 32, s3
	s_min_i32 s7, s7, 8
	s_abs_i32 s9, s7
	v_cvt_f32_u32_e32 v2, s9
	s_sub_i32 s19, 0, s9
	s_and_b32 s1, s1, 0xffffff80
	s_sub_i32 s0, s0, s1
	v_rcp_iflag_f32_e32 v2, v2
	s_abs_i32 s1, s0
	s_xor_b32 s18, s0, s7
	s_ashr_i32 s18, s18, 31
	v_mul_f32_e32 v2, 0x4f7ffffe, v2
	v_cvt_u32_f32_e32 v2, v2
	s_nop 0
	v_readfirstlane_b32 s20, v2
	s_mul_i32 s19, s19, s20
	s_mul_hi_u32 s19, s20, s19
	s_add_i32 s20, s20, s19
	s_mul_hi_u32 s19, s1, s20
	s_mul_i32 s20, s19, s9
	s_sub_i32 s1, s1, s20
	s_add_i32 s21, s19, 1
	s_sub_i32 s20, s1, s9
	s_cmp_ge_u32 s1, s9
	s_cselect_b32 s19, s21, s19
	s_cselect_b32 s1, s20, s1
	s_add_i32 s20, s19, 1
	s_cmp_ge_u32 s1, s9
	s_cselect_b32 s1, s20, s19
	s_xor_b32 s1, s1, s18
	s_sub_i32 s18, s1, s18
	s_mul_i32 s1, s18, s7
	s_sub_i32 s0, s0, s1
	s_add_i32 s20, s3, s0

; #define PG8_BAR __builtin_amdgcn_s_barrier()
;     __device__ bool next(int i, Unit& u) const {
;         const long L = (long)i * G + c; if (L >= nwg) return false;
;         int wgid = (int)L; { const int q = nwg / NXCD, r = nwg % NXCD, xcd = wgid % NXCD, off = wgid / NXCD; wgid = (xcd < r ? xcd * (q + 1) : r * (q + 1) + (xcd - r) * q) + off; }
;         const int nig = WGM * nN, gid = wgid / nig, fm = gid * WGM, gsz = (nM - fm) < WGM ? (nM - fm) : WGM;
;         u.pm = fm + ((wgid % nig) % gsz); u.pn = (wgid % nig) / gsz; return true;
;     }
; template <class Epi>
; __device__ __forceinline__ void gemm_phase(LAS unsigned char* lds, const Gemm g, const StaticOrder& S, const Epi& E) {
;     const int tid = launder(threadIdx.x), wid = __builtin_amdgcn_readfirstlane(tid >> 6), lane = tid & 63, wr = wid >> 2, wc = wid & 3, fr = lane & 15, fq = lane >> 4;
;     const int K = g.K, nt = K / BK;
;     unsigned voffA[2], voffB[2];
; #pragma unroll
;     for (int i = 0; i < 2; ++i) { int R, C; stage_rc(tid * 16 + i * 8192, R, C); const int Rb = Epi::PERM ? ((R & ~31) + perm32(R & 31)) : R;
;         voffA[i] = (unsigned)(R * g.lda + C) * 2u; voffB[i] = (unsigned)(Rb * g.ldb + C) * 2u; }
;     const size_t kstep = (size_t)(BK * 2);
;     const size_t hstepA = (size_t)HALF * g.lda * 2, hstepB = (size_t)HALF * g.ldb * 2;
;     const size_t tstepA = 2 * hstepA, tstepB = 2 * hstepB;
;     const unsigned ldsw = (unsigned)wid * 1024u;
;     const int aoff = lds_byte(wr * 64 + fr, fq * 8), boff = lds_byte(wc * 32 + fr, fq * 8);
;     ...
;     Unit cur, nxt; int ui = 0;
;     if (!S.next(0, cur)) return;
;     f32x4 acc[2][2][4][2];
; #pragma unroll
;     for (int a = 0; a < 2; ++a)
; #pragma unroll
;         for (int b = 0; b < 2; ++b)
; #pragma unroll
;             for (int m = 0; m < 4; ++m)
; #pragma unroll
;                 for (int n = 0; n < 2; ++n) acc[a][b][m][n] = (f32x4){0.f, 0.f, 0.f, 0.f};
;     bf16x8 At[4][2], B0[2][2], B1[2][2];
;     const char* cA = PG8_UA(cur); const char* cB = PG8_UB(cur);
;     PG8_STAGE(PG8_SB(0, 0), cB, voffB); PG8_STAGE(PG8_SB(0, 1), cB + hstepB, voffB); PG8_STAGE(PG8_SA(0, 0), cA, voffA); PG8_STAGE(PG8_SA(0, 1), cA + hstepA, voffA);
;     if (wr == 1) PG8_BAR;
;     PG8_WAIT_V(2); PG8_BAR;
;     PG8_STAGE(PG8_SB(1, 0), cB + kstep, voffB); PG8_STAGE(PG8_SA(1, 0), cA + kstep, voffA); PG8_STAGE(PG8_SB(1, 1), cB + hstepB + kstep, voffB);
.LBB0_669:
	v_bfe_i32 v4, v1, 27, 1
	v_lshlrev_b32_e32 v2, 4, v1
	v_lshrrev_b32_e32 v4, 22, v4
	v_add_u32_e32 v4, v2, v4
	v_and_b32_e32 v4, 0xfffffc00, v4
	v_ashrrev_i32_e32 v3, 31, v1
	v_sub_u32_e32 v4, v2, v4
	v_lshrrev_b32_e32 v3, 26, v3
	v_lshrrev_b32_e32 v5, 4, v4
	v_add_u32_e32 v3, v1, v3
	v_bitop3_b32 v5, v5, v4, 32 bitop3:0x6c
	v_ashrrev_i32_e32 v4, 31, v4
	v_ashrrev_i32_e32 v3, 6, v3
	v_lshrrev_b32_e32 v4, 26, v4
	v_lshlrev_b32_e32 v6, 3, v3
	v_add_u32_e32 v4, v5, v4
	v_and_b32_e32 v6, -16, v6
	v_ashrrev_i32_e32 v4, 6, v4
	v_add_u32_e32 v6, v4, v6
	v_mul_i32_i24_e32 v4, 64, v4
	v_lshlrev_b32_e32 v3, 5, v3
	v_sub_u32_e32 v4, v5, v4
	v_mov_b32_e32 v7, 1
	v_and_b32_e32 v3, 32, v3
	v_ashrrev_i16_sdwa v4, v7, sext(v4) dst_sel:DWORD dst_unused:UNUSED_PAD src0_sel:DWORD src1_sel:BYTE_0
	v_add_u32_sdwa v3, v3, sext(v4) dst_sel:DWORD dst_unused:UNUSED_PAD src0_sel:DWORD src1_sel:WORD_0
	v_lshlrev_b32_e32 v4, 12, v6
	v_add_u32_e32 v2, 0x2000, v2
	v_lshl_add_u32 v130, v3, 1, v4
	v_ashrrev_i32_e32 v3, 31, v2
	v_lshrrev_b32_e32 v3, 22, v3
	v_add_u32_e32 v3, v2, v3
	v_ashrrev_i32_e32 v3, 10, v3
	v_mul_i32_i24_e32 v4, 0x400, v3
	v_sub_u32_e32 v2, v2, v4
	v_lshrrev_b32_e32 v4, 4, v2
	v_bitop3_b32 v2, v4, v2, 32 bitop3:0x6c
	v_ashrrev_i32_e32 v5, 31, v2
	v_lshrrev_b32_e32 v5, 26, v5
	s_movk_i32 s5, 0xf200
	v_add_u32_e32 v5, v2, v5
	v_mad_u64_u32 v[132:133], s[12:13], v6, s5, v[130:131]
	v_lshlrev_b32_e32 v4, 3, v3
	v_ashrrev_i32_e32 v6, 6, v5
	v_and_b32_e32 v5, 0xc0, v5
	v_and_b32_e32 v4, -16, v4
	v_lshlrev_b32_e32 v3, 5, v3
	v_sub_u32_e32 v2, v2, v5
	v_add_u32_e32 v4, v6, v4
	v_and_b32_e32 v3, 32, v3
	v_ashrrev_i16_sdwa v2, v7, sext(v2) dst_sel:DWORD dst_unused:UNUSED_PAD src0_sel:DWORD src1_sel:BYTE_0
	s_add_i32 s0, s0, s7
	s_bfe_u32 s100, s0, 0x10006
	s_bfe_u32 s101, s0, 0x40002
	s_andn2_b32 s0, s0, 0x7c
	s_lshl_b32 s100, s100, 2
	s_lshl_b32 s101, s101, 3
	s_or_b32 s0, s0, s100
	s_or_b32 s0, s0, s101
	v_add_u32_sdwa v2, v3, sext(v2) dst_sel:DWORD dst_unused:UNUSED_PAD src0_sel:DWORD src1_sel:WORD_0
	v_lshlrev_b32_e32 v3, 12, v4
	s_ashr_i32 s7, s0, 31
	v_lshl_add_u32 v134, v2, 1, v3
	s_lshr_b32 s7, s7, 25
	v_mad_u64_u32 v[136:137], s[12:13], v4, s5, v[134:135]
	s_add_i32 s7, s0, s7
	s_ashr_i32 s12, s7, 7
	s_and_b32 s7, s7, 0xff80
	s_sub_i32 s0, s0, s7
	s_bfe_i32 s7, s0, 0x80000
	s_bfe_u32 s7, s7, 0x3000c
	s_add_i32 s7, s0, s7
	s_lshl_b32 s13, s12, 3
	s_bfe_i32 s12, s7, 0x80000
	s_and_b32 s7, s7, 0xf8
	s_sub_i32 s0, s0, s7
	s_sext_i32_i16 s14, s12
	s_sext_i32_i8 s0, s0
	s_add_i32 s28, s13, s0
	s_ashr_i32 s0, s14, 3
	s_lshl_b32 s7, s0, 7
	s_lshr_b32 s12, s14, 3
	s_and_b32 s14, s7, 0xffffff00
	s_ashr_i32 s5, s6, 6
	s_ashr_i32 s29, s28, 31
	s_ashr_i32 s15, s14, 31
	s_bfe_i64 s[12:13], s[12:13], 0x100000
	s_ashr_i32 s4, s6, 8
	s_lshl_b32 s11, s5, 10
	s_lshl_b64 s[16:17], s[28:29], 20
	s_lshl_b64 s[18:19], s[14:15], 1
	s_lshl_b64 s[12:13], s[12:13], 17
	v_readlane_b32 s14, v254, 33
	v_readlane_b32 s15, v254, 34
	s_add_u32 s34, s14, s12
	s_addc_u32 s35, s15, s13
	s_add_i32 s14, s11, 0
	s_add_i32 m0, s14, 0x10000
	v_readlane_b32 s12, v254, 19
	global_load_lds_dwordx4 v132, s[34:35]
	s_add_i32 m0, s14, 0x12000
	v_readlane_b32 s13, v254, 20
	s_add_u32 s7, s12, s16
	s_addc_u32 s15, s13, s17
	s_add_u32 s12, s34, 0x10000
	global_load_lds_dwordx4 v136, s[34:35]
	s_addc_u32 s13, s35, 0
	s_add_i32 m0, s14, 0x14000
	s_nop 0
	global_load_lds_dwordx4 v132, s[12:13]
	s_add_i32 m0, s14, 0x16000
	s_add_u32 s30, s7, s18
	s_addc_u32 s31, s15, s19
	s_add_i32 s15, s14, 0x2000
	global_load_lds_dwordx4 v136, s[12:13]
	s_mov_b32 m0, s14
	s_add_u32 s12, s30, 0x80000
	global_load_lds_dwordx4 v130, s[30:31]
	s_mov_b32 m0, s15
	s_addc_u32 s13, s31, 0
	s_add_i32 s29, s14, 0x4000
	global_load_lds_dwordx4 v134, s[30:31]
	s_mov_b32 m0, s29
	s_add_i32 s42, s14, 0x6000
	global_load_lds_dwordx4 v130, s[12:13]
	s_mov_b32 m0, s42
	s_cmp_eq_u32 s4, 1
	global_load_lds_dwordx4 v134, s[12:13]
	s_cselect_b64 s[12:13], -1, 0
	s_cmp_lg_u32 s4, 1
	s_cbranch_scc1 .LBB0_671
	s_barrier

;     __device__ bool next(int i, Unit& u) const {
;         const long L = (long)i * G + c; if (L >= nwg) return false;
;         int wgid = (int)L; { const int q = nwg / NXCD, r = nwg % NXCD, xcd = wgid % NXCD, off = wgid / NXCD; wgid = (xcd < r ? xcd * (q + 1) : r * (q + 1) + (xcd - r) * q) + off; }
;         const int nig = WGM * nN, gid = wgid / nig, fm = gid * WGM, gsz = (nM - fm) < WGM ? (nM - fm) : WGM;
;         u.pm = fm + ((wgid % nig) % gsz); u.pn = (wgid % nig) / gsz; return true;
;     }
.LBB0_679:
	s_ashr_i32 s1, s1, 3
	s_add_i32 s1, s20, s1
	s_bfe_u32 s100, s1, 0x10006
	s_bfe_u32 s101, s1, 0x40002
	s_andn2_b32 s1, s1, 0x7c
	s_lshl_b32 s100, s100, 2
	s_lshl_b32 s101, s101, 3
	s_or_b32 s1, s1, s100
	s_or_b32 s1, s1, s101
	s_ashr_i32 s3, s1, 31
	s_lshr_b32 s3, s3, 25
	s_add_i32 s3, s1, s3
	s_ashr_i32 s4, s3, 7
	s_lshl_b32 s4, s4, 3
	s_sub_i32 s5, 32, s4
	s_min_i32 s5, s5, 8
	s_abs_i32 s20, s5
	v_cvt_f32_u32_e32 v2, s20
	s_sub_i32 s22, 0, s20
	s_and_b32 s3, s3, 0xffffff80
	s_sub_i32 s1, s1, s3
	v_rcp_iflag_f32_e32 v2, v2
	s_abs_i32 s3, s1
	s_xor_b32 s21, s1, s5
	s_ashr_i32 s21, s21, 31
	v_mul_f32_e32 v2, 0x4f7ffffe, v2
	v_cvt_u32_f32_e32 v2, v2
	s_nop 0
	v_readfirstlane_b32 s23, v2
	s_mul_i32 s22, s22, s23
	s_mul_hi_u32 s22, s23, s22
	s_add_i32 s23, s23, s22
	s_mul_hi_u32 s22, s3, s23
	s_mul_i32 s23, s22, s20
	s_sub_i32 s3, s3, s23
	s_add_i32 s24, s22, 1
	s_sub_i32 s23, s3, s20
	s_cmp_ge_u32 s3, s20
	s_cselect_b32 s22, s24, s22
	s_cselect_b32 s3, s23, s3
	s_add_i32 s23, s22, 1
	s_cmp_ge_u32 s3, s20
	s_cselect_b32 s3, s23, s22
	s_xor_b32 s3, s3, s21
	s_sub_i32 s20, s3, s21
	s_mul_i32 s3, s20, s5
	s_sub_i32 s1, s1, s3
	s_add_i32 s22, s4, s1

;     __device__ bool next(int i, Unit& u) const {
;         const long L = (long)i * G + c; if (L >= nwg) return false;
;         int wgid = (int)L; { const int q = nwg / NXCD, r = nwg % NXCD, xcd = wgid % NXCD, off = wgid / NXCD; wgid = (xcd < r ? xcd * (q + 1) : r * (q + 1) + (xcd - r) * q) + off; }
;         const int nig = WGM * nN, gid = wgid / nig, fm = gid * WGM, gsz = (nM - fm) < WGM ? (nM - fm) : WGM;
;         u.pm = fm + ((wgid % nig) % gsz); u.pn = (wgid % nig) / gsz; return true;
;     }
.LBB0_996:
	s_ashr_i32 s1, s1, 3
	s_add_i32 s1, s8, s1
	s_bfe_u32 s100, s1, 0x10005
	s_bfe_u32 s101, s1, 0x30002
	s_andn2_b32 s1, s1, 0x3c
	s_lshl_b32 s100, s100, 2
	s_lshl_b32 s101, s101, 3
	s_or_b32 s1, s1, s100
	s_or_b32 s1, s1, s101
	s_ashr_i32 s3, s1, 31
	s_lshr_b32 s3, s3, 26
	s_add_i32 s3, s1, s3
	s_ashr_i32 s6, s3, 6
	s_and_b32 s3, s3, 0xffc0
	s_sub_i32 s1, s1, s3
	s_bfe_i32 s3, s1, 0x80000
	s_bfe_u32 s3, s3, 0x3000c
	s_add_i32 s3, s1, s3
	s_bfe_i32 s7, s3, 0x80000
	s_and_b32 s3, s3, 0xf8
	s_sub_i32 s1, s1, s3
	s_lshl_b32 s6, s6, 3
	s_sext_i32_i16 s7, s7
	s_sext_i32_i8 s1, s1
	s_add_i32 s24, s6, s1
	s_ashr_i32 s6, s7, 3

;     __device__ bool next(int i, Unit& u) const {
;         const long L = (long)i * G + c; if (L >= nwg) return false;
;         int wgid = (int)L; { const int q = nwg / NXCD, r = nwg % NXCD, xcd = wgid % NXCD, off = wgid / NXCD; wgid = (xcd < r ? xcd * (q + 1) : r * (q + 1) + (xcd - r) * q) + off; }
;         const int nig = WGM * nN, gid = wgid / nig, fm = gid * WGM, gsz = (nM - fm) < WGM ? (nM - fm) : WGM;
;         u.pm = fm + ((wgid % nig) % gsz); u.pn = (wgid % nig) / gsz; return true;
;     }
.LBB0_1008:
	s_ashr_i32 s1, s1, 3
	s_add_i32 s1, s7, s1
	s_bfe_u32 s100, s1, 0x10005
	s_bfe_u32 s101, s1, 0x30002
	s_andn2_b32 s1, s1, 0x3c
	s_lshl_b32 s100, s100, 2
	s_lshl_b32 s101, s101, 3
	s_or_b32 s1, s1, s100
	s_or_b32 s1, s1, s101
	s_ashr_i32 s3, s1, 31
	s_lshr_b32 s3, s3, 26
	s_add_i32 s3, s1, s3
	s_ashr_i32 s7, s3, 6
	s_lshl_b32 s7, s7, 3
	s_sub_i32 s14, 32, s7
	s_min_i32 s14, s14, 8
	s_abs_i32 s15, s14
	v_cvt_f32_u32_e32 v2, s15
	s_sub_i32 s17, 0, s15
	s_andn2_b32 s3, s3, 63
	s_sub_i32 s1, s1, s3
	v_rcp_iflag_f32_e32 v2, v2
	s_abs_i32 s3, s1
	s_xor_b32 s16, s1, s14
	s_ashr_i32 s16, s16, 31
	v_mul_f32_e32 v2, 0x4f7ffffe, v2
	v_cvt_u32_f32_e32 v2, v2
	s_nop 0
	v_readfirstlane_b32 s18, v2
	s_mul_i32 s17, s17, s18
	s_mul_hi_u32 s17, s18, s17
	s_add_i32 s18, s18, s17
	s_mul_hi_u32 s17, s3, s18
	s_mul_i32 s18, s17, s15
	s_sub_i32 s3, s3, s18
	s_add_i32 s19, s17, 1
	s_sub_i32 s18, s3, s15
	s_cmp_ge_u32 s3, s15
	s_cselect_b32 s17, s19, s17
	s_cselect_b32 s3, s18, s3
	s_add_i32 s18, s17, 1
	s_cmp_ge_u32 s3, s15
	s_cselect_b32 s3, s18, s17
	s_xor_b32 s3, s3, s16
	s_sub_i32 s16, s3, s16
	s_mul_i32 s3, s16, s14
	s_sub_i32 s1, s1, s3
	s_add_i32 s18, s7, s1

; #define PG8_BAR __builtin_amdgcn_s_barrier()
;     __device__ bool next(int i, Unit& u) const {
;         const long L = (long)i * G + c; if (L >= nwg) return false;
;         int wgid = (int)L; { const int q = nwg / NXCD, r = nwg % NXCD, xcd = wgid % NXCD, off = wgid / NXCD; wgid = (xcd < r ? xcd * (q + 1) : r * (q + 1) + (xcd - r) * q) + off; }
;         const int nig = WGM * nN, gid = wgid / nig, fm = gid * WGM, gsz = (nM - fm) < WGM ? (nM - fm) : WGM;
;         u.pm = fm + ((wgid % nig) % gsz); u.pn = (wgid % nig) / gsz; return true;
;     }
; template <class Epi>
; __device__ __forceinline__ void gemm_phase(LAS unsigned char* lds, const Gemm g, const StaticOrder& S, const Epi& E) {
;     const int tid = launder(threadIdx.x), wid = __builtin_amdgcn_readfirstlane(tid >> 6), lane = tid & 63, wr = wid >> 2, wc = wid & 3, fr = lane & 15, fq = lane >> 4;
;     const int K = g.K, nt = K / BK;
;     unsigned voffA[2], voffB[2];
; #pragma unroll
;     for (int i = 0; i < 2; ++i) { int R, C; stage_rc(tid * 16 + i * 8192, R, C); const int Rb = Epi::PERM ? ((R & ~31) + perm32(R & 31)) : R;
;         voffA[i] = (unsigned)(R * g.lda + C) * 2u; voffB[i] = (unsigned)(Rb * g.ldb + C) * 2u; }
;     const size_t kstep = (size_t)(BK * 2);
;     const size_t hstepA = (size_t)HALF * g.lda * 2, hstepB = (size_t)HALF * g.ldb * 2;
;     const size_t tstepA = 2 * hstepA, tstepB = 2 * hstepB;
;     const unsigned ldsw = (unsigned)wid * 1024u;
;     const int aoff = lds_byte(wr * 64 + fr, fq * 8), boff = lds_byte(wc * 32 + fr, fq * 8);
;     ...
;     Unit cur, nxt; int ui = 0;
;     if (!S.next(0, cur)) return;
;     f32x4 acc[2][2][4][2];
; #pragma unroll
;     for (int a = 0; a < 2; ++a)
; #pragma unroll
;         for (int b = 0; b < 2; ++b)
; #pragma unroll
;             for (int m = 0; m < 4; ++m)
; #pragma unroll
;                 for (int n = 0; n < 2; ++n) acc[a][b][m][n] = (f32x4){0.f, 0.f, 0.f, 0.f};
;     bf16x8 At[4][2], B0[2][2], B1[2][2];
;     const char* cA = PG8_UA(cur); const char* cB = PG8_UB(cur);
;     PG8_STAGE(PG8_SB(0, 0), cB, voffB); PG8_STAGE(PG8_SB(0, 1), cB + hstepB, voffB); PG8_STAGE(PG8_SA(0, 0), cA, voffA); PG8_STAGE(PG8_SA(0, 1), cA + hstepA, voffA);
;     if (wr == 1) PG8_BAR;
;     PG8_WAIT_V(2); PG8_BAR;
;     PG8_STAGE(PG8_SB(1, 0), cB + kstep, voffB); PG8_STAGE(PG8_SA(1, 0), cA + kstep, voffA); PG8_STAGE(PG8_SB(1, 1), cB + hstepB + kstep, voffB);
.LBB0_1095:
	s_waitcnt lgkmcnt(0)
	v_ashrrev_i32_e32 v3, 31, v1
	v_lshrrev_b32_e32 v3, 26, v3
	v_add_u32_e32 v3, v1, v3
	v_ashrrev_i32_e32 v10, 6, v3
	v_bfe_i32 v3, v1, 27, 1
	v_lshlrev_b32_e32 v2, 4, v1
	v_lshrrev_b32_e32 v3, 22, v3
	v_add_u32_e32 v3, v2, v3
	v_and_b32_e32 v3, 0xfffffc00, v3
	v_sub_u32_e32 v3, v2, v3
	v_lshrrev_b32_e32 v4, 4, v3
	v_bitop3_b32 v4, v4, v3, 32 bitop3:0x6c
	v_ashrrev_i32_e32 v3, 31, v3
	v_lshrrev_b32_e32 v3, 26, v3
	v_add_u32_e32 v3, v4, v3
	v_ashrrev_i32_e32 v11, 6, v3
	v_lshlrev_b32_e32 v5, 3, v10
	v_mul_i32_i24_e32 v6, 64, v11
	v_and_b32_e32 v5, -16, v5
	v_sub_u32_e32 v4, v4, v6
	v_mov_b32_e32 v8, 1
	v_add_u32_e32 v3, v11, v5
	v_lshlrev_b32_e32 v5, 5, v10
	v_ashrrev_i16_sdwa v4, v8, sext(v4) dst_sel:DWORD dst_unused:UNUSED_PAD src0_sel:DWORD src1_sel:BYTE_0
	v_and_b32_e32 v5, 32, v5
	v_bfe_i32 v12, v4, 0, 16
	v_and_b32_e32 v7, 3, v11
	s_mov_b32 s7, 0xfffe0
	v_add_lshl_u32 v5, v5, v12, 1
	v_add_u32_e32 v2, 0x2000, v2
	v_lshlrev_b32_e32 v4, 1, v3
	v_lshrrev_b32_e32 v6, 2, v3
	v_and_or_b32 v7, v3, s7, v7
	v_lshl_add_u32 v146, v3, 12, v5
	v_ashrrev_i32_e32 v3, 31, v2
	v_lshrrev_b32_e32 v3, 22, v3
	v_add_u32_e32 v3, v2, v3
	v_ashrrev_i32_e32 v13, 10, v3
	v_mul_i32_i24_e32 v3, 0x400, v13
	v_sub_u32_e32 v2, v2, v3
	v_and_b32_e32 v4, 24, v4
	v_and_b32_e32 v6, 4, v6
	v_lshrrev_b32_e32 v3, 4, v2
	v_or3_b32 v4, v7, v6, v4
	v_bitop3_b32 v2, v3, v2, 32 bitop3:0x6c
	v_lshl_add_u32 v148, v4, 12, v5
	v_ashrrev_i32_e32 v4, 31, v2
	v_lshrrev_b32_e32 v4, 26, v4
	s_add_i32 s4, s6, s4
	s_bfe_u32 s100, s4, 0x10005
	s_bfe_u32 s101, s4, 0x30002
	s_andn2_b32 s4, s4, 0x3c
	s_lshl_b32 s100, s100, 2
	s_lshl_b32 s101, s101, 3
	s_or_b32 s4, s4, s100
	s_or_b32 s4, s4, s101
	v_lshlrev_b32_e32 v3, 3, v13
	v_add_u32_e32 v4, v2, v4
	s_ashr_i32 s6, s4, 31
	v_and_b32_e32 v3, -16, v3
	v_ashrrev_i32_e32 v14, 6, v4
	s_lshr_b32 s6, s6, 26
	v_add_u32_e32 v3, v14, v3
	v_and_b32_e32 v6, 3, v14
	s_add_i32 s6, s4, s6
	v_and_or_b32 v6, v3, s7, v6
	s_ashr_i32 s7, s6, 6
	s_and_b32 s6, s6, 0xffc0
	s_sub_i32 s6, s4, s6
	s_bfe_i32 s4, s6, 0x80000
	s_bfe_u32 s4, s4, 0x3000c
	s_add_i32 s8, s6, s4
	s_bfe_i32 s4, s8, 0x80000
	s_and_b32 s8, s8, 0xf8
	s_sub_i32 s6, s6, s8
	s_lshl_b32 s7, s7, 3
	s_sext_i32_i16 s4, s4
	s_sext_i32_i8 s6, s6
	s_ashr_i32 s5, s3, 6
	s_lshr_b32 s4, s4, 3
	s_add_i32 s6, s7, s6
	v_and_b32_e32 v4, 0xc0, v4
	s_ashr_i32 s7, s6, 31
	s_bfe_i64 s[12:13], s[4:5], 0x100000
	v_sub_u32_e32 v2, v2, v4
	s_ashr_i32 s10, s3, 8
	s_lshl_b32 s42, s5, 10
	s_lshl_b64 s[8:9], s[6:7], 20
	s_lshl_b64 s[12:13], s[12:13], 20
	v_ashrrev_i16_sdwa v2, v8, sext(v2) dst_sel:DWORD dst_unused:UNUSED_PAD src0_sel:DWORD src1_sel:BYTE_0
	s_add_u32 s34, s80, s12
	v_lshlrev_b32_e32 v5, 5, v13
	v_bfe_i32 v15, v2, 0, 16
	v_lshlrev_b32_e32 v2, 1, v3
	v_lshrrev_b32_e32 v4, 2, v3
	s_addc_u32 s35, s81, s13
	s_add_i32 s70, s42, 0
	v_and_b32_e32 v5, 32, v5
	v_and_b32_e32 v2, 24, v2
	v_and_b32_e32 v4, 4, v4
	s_add_i32 m0, s70, 0x10000
	v_or3_b32 v2, v6, v4, v2
	v_add_lshl_u32 v4, v5, v15, 1
	global_load_lds_dwordx4 v148, s[34:35]
	s_add_i32 m0, s70, 0x12000
	v_lshl_add_u32 v152, v2, 12, v4
	s_add_u32 s12, s34, 0x80000
	global_load_lds_dwordx4 v152, s[34:35]
	s_addc_u32 s13, s35, 0
	s_add_i32 m0, s70, 0x14000
	v_lshl_add_u32 v150, v3, 12, v4
	global_load_lds_dwordx4 v148, s[12:13]
	s_add_i32 m0, s70, 0x16000
	s_add_u32 s68, s54, s8
	s_addc_u32 s69, s55, s9
	s_add_i32 s91, s70, 0x2000
	global_load_lds_dwordx4 v152, s[12:13]
	s_mov_b32 m0, s70
	s_add_u32 s8, s68, 0x80000
	global_load_lds_dwordx4 v146, s[68:69]
	s_mov_b32 m0, s91
	s_addc_u32 s9, s69, 0
	s_add_i32 s62, s70, 0x4000
	global_load_lds_dwordx4 v150, s[68:69]
	s_mov_b32 m0, s62
	s_add_i32 s63, s70, 0x6000
	global_load_lds_dwordx4 v146, s[8:9]
	s_mov_b32 m0, s63
	v_mov_b32_e32 v149, v0
	global_load_lds_dwordx4 v150, s[8:9]
	v_mov_b32_e32 v153, v0
	v_mov_b32_e32 v147, v0
	v_mov_b32_e32 v151, v0
	s_cmp_eq_u32 s10, 1
	v_lshl_add_u64 v[8:9], s[34:35], 0, v[148:149]
	v_lshl_add_u64 v[6:7], s[34:35], 0, v[152:153]
	v_lshl_add_u64 v[2:3], s[68:69], 0, v[146:147]
	s_cselect_b64 s[8:9], -1, 0
	s_cmp_lg_u32 s10, 1
	v_lshl_add_u64 v[4:5], s[68:69], 0, v[150:151]
	s_cbranch_scc1 .LBB0_1097
	s_barrier

;     __device__ bool next(int i, Unit& u) const {
;         const long L = (long)i * G + c; if (L >= nwg) return false;
;         int wgid = (int)L; { const int q = nwg / NXCD, r = nwg % NXCD, xcd = wgid % NXCD, off = wgid / NXCD; wgid = (xcd < r ? xcd * (q + 1) : r * (q + 1) + (xcd - r) * q) + off; }
;         const int nig = WGM * nN, gid = wgid / nig, fm = gid * WGM, gsz = (nM - fm) < WGM ? (nM - fm) : WGM;
;         u.pm = fm + ((wgid % nig) % gsz); u.pn = (wgid % nig) / gsz; return true;
;     }
.LBB0_1105:
	s_ashr_i32 s3, s3, 3
	s_add_i32 s3, s14, s3
	s_bfe_u32 s100, s3, 0x10005
	s_bfe_u32 s101, s3, 0x30002
	s_andn2_b32 s3, s3, 0x3c
	s_lshl_b32 s100, s100, 2
	s_lshl_b32 s101, s101, 3
	s_or_b32 s3, s3, s100
	s_or_b32 s3, s3, s101
	s_ashr_i32 s7, s3, 31
	s_lshr_b32 s7, s7, 26
	s_add_i32 s7, s3, s7
	s_ashr_i32 s12, s7, 6
	s_lshl_b32 s13, s12, 3
	s_sub_i32 s12, 32, s13
	s_min_i32 s14, s12, 8
	s_abs_i32 s12, s14
	v_cvt_f32_u32_e32 v2, s12
	s_sub_i32 s40, 0, s12
	s_andn2_b32 s7, s7, 63
	s_sub_i32 s3, s3, s7
	v_rcp_iflag_f32_e32 v2, v2
	s_abs_i32 s7, s3
	s_xor_b32 s15, s3, s14
	s_ashr_i32 s15, s15, 31
	v_mul_f32_e32 v2, 0x4f7ffffe, v2
	v_cvt_u32_f32_e32 v2, v2
	s_nop 0
	v_readfirstlane_b32 s41, v2
	s_mul_i32 s40, s40, s41
	s_mul_hi_u32 s40, s41, s40
	s_add_i32 s41, s41, s40
	s_mul_hi_u32 s40, s7, s41
	s_mul_i32 s41, s40, s12
	s_sub_i32 s7, s7, s41
	s_add_i32 s44, s40, 1
	s_sub_i32 s41, s7, s12
	s_cmp_ge_u32 s7, s12
	s_cselect_b32 s40, s44, s40
	s_cselect_b32 s7, s41, s7
	s_add_i32 s41, s40, 1
	s_cmp_ge_u32 s7, s12
	s_cselect_b32 s7, s41, s40
	s_xor_b32 s7, s7, s15
	s_sub_i32 s12, s7, s15
	s_mul_i32 s7, s12, s14
	s_sub_i32 s3, s3, s7
	s_add_i32 s86, s13, s3

;     __device__ bool next(int i, Unit& u) const {
;         const long L = (long)i * G + c; if (L >= nwg) return false;
;         int wgid = (int)L; { const int q = nwg / NXCD, r = nwg % NXCD, xcd = wgid % NXCD, off = wgid / NXCD; wgid = (xcd < r ? xcd * (q + 1) : r * (q + 1) + (xcd - r) * q) + off; }
;         const int nig = WGM * nN, gid = wgid / nig, fm = gid * WGM, gsz = (nM - fm) < WGM ? (nM - fm) : WGM;
;         u.pm = fm + ((wgid % nig) % gsz); u.pn = (wgid % nig) / gsz; return true;
;     }
.LBB0_1310:
	s_ashr_i32 s6, s8, 3
	s_add_i32 s6, s10, s6
	s_bfe_u32 s100, s6, 0x10006
	s_bfe_u32 s101, s6, 0x40002
	s_andn2_b32 s6, s6, 0x7c
	s_lshl_b32 s100, s100, 2
	s_lshl_b32 s101, s101, 3
	s_or_b32 s6, s6, s100
	s_or_b32 s6, s6, s101
	s_ashr_i32 s7, s6, 31
	s_lshr_b32 s7, s7, 25
	s_add_i32 s7, s6, s7
	s_ashr_i32 s8, s7, 7
	s_and_b32 s7, s7, 0xff80
	s_sub_i32 s6, s6, s7
	s_bfe_i32 s7, s6, 0x80000
	s_bfe_u32 s7, s7, 0x3000c
	s_add_i32 s7, s6, s7
	s_bfe_i32 s9, s7, 0x80000
	s_and_b32 s7, s7, 0xf8
	s_sub_i32 s6, s6, s7
	s_lshl_b32 s8, s8, 3
	s_sext_i32_i16 s9, s9
	s_sext_i32_i8 s6, s6
	s_add_i32 s22, s8, s6
	s_ashr_i32 s6, s9, 3

;     __device__ bool next(int i, Unit& u) const {
;         const long L = (long)i * G + c; if (L >= nwg) return false;
;         int wgid = (int)L; { const int q = nwg / NXCD, r = nwg % NXCD, xcd = wgid % NXCD, off = wgid / NXCD; wgid = (xcd < r ? xcd * (q + 1) : r * (q + 1) + (xcd - r) * q) + off; }
;         const int nig = WGM * nN, gid = wgid / nig, fm = gid * WGM, gsz = (nM - fm) < WGM ? (nM - fm) : WGM;
;         u.pm = fm + ((wgid % nig) % gsz); u.pn = (wgid % nig) / gsz; return true;
;     }
.LBB0_1322:
	s_ashr_i32 s3, s3, 3
	s_add_i32 s3, s16, s3
	s_bfe_u32 s100, s3, 0x10006
	s_bfe_u32 s101, s3, 0x40002
	s_andn2_b32 s3, s3, 0x7c
	s_lshl_b32 s100, s100, 2
	s_lshl_b32 s101, s101, 3
	s_or_b32 s3, s3, s100
	s_or_b32 s3, s3, s101
	s_ashr_i32 s7, s3, 31
	s_lshr_b32 s7, s7, 25
	s_add_i32 s7, s3, s7
	s_ashr_i32 s12, s7, 7
	s_lshl_b32 s13, s12, 3
	s_sub_i32 s12, 32, s13
	s_min_i32 s16, s12, 8
	s_abs_i32 s12, s16
	v_cvt_f32_u32_e32 v2, s12
	s_sub_i32 s18, 0, s12
	s_and_b32 s7, s7, 0xffffff80
	s_sub_i32 s3, s3, s7
	v_rcp_iflag_f32_e32 v2, v2
	s_abs_i32 s7, s3
	s_xor_b32 s17, s3, s16
	s_ashr_i32 s17, s17, 31
	v_mul_f32_e32 v2, 0x4f7ffffe, v2
	v_cvt_u32_f32_e32 v2, v2
	s_nop 0
	v_readfirstlane_b32 s19, v2
	s_mul_i32 s18, s18, s19
	s_mul_hi_u32 s18, s19, s18
	s_add_i32 s19, s19, s18
	s_mul_hi_u32 s18, s7, s19
	s_mul_i32 s19, s18, s12
	s_sub_i32 s7, s7, s19
	s_add_i32 s20, s18, 1
	s_sub_i32 s19, s7, s12
	s_cmp_ge_u32 s7, s12
	s_cselect_b32 s18, s20, s18
	s_cselect_b32 s7, s19, s7
	s_add_i32 s19, s18, 1
	s_cmp_ge_u32 s7, s12
	s_cselect_b32 s7, s19, s18
	s_xor_b32 s7, s7, s17
	s_sub_i32 s12, s7, s17
	s_mul_i32 s7, s12, s16
	s_sub_i32 s3, s3, s7
	s_add_i32 s16, s13, s3

; #define PG8_BAR __builtin_amdgcn_s_barrier()
;     __device__ bool next(int i, Unit& u) const {
;         const long L = (long)i * G + c; if (L >= nwg) return false;
;         int wgid = (int)L; { const int q = nwg / NXCD, r = nwg % NXCD, xcd = wgid % NXCD, off = wgid / NXCD; wgid = (xcd < r ? xcd * (q + 1) : r * (q + 1) + (xcd - r) * q) + off; }
;         const int nig = WGM * nN, gid = wgid / nig, fm = gid * WGM, gsz = (nM - fm) < WGM ? (nM - fm) : WGM;
;         u.pm = fm + ((wgid % nig) % gsz); u.pn = (wgid % nig) / gsz; return true;
;     }
; template <class Epi>
; __device__ __forceinline__ void gemm_phase(LAS unsigned char* lds, const Gemm g, const StaticOrder& S, const Epi& E) {
;     const int tid = launder(threadIdx.x), wid = __builtin_amdgcn_readfirstlane(tid >> 6), lane = tid & 63, wr = wid >> 2, wc = wid & 3, fr = lane & 15, fq = lane >> 4;
;     const int K = g.K, nt = K / BK;
;     unsigned voffA[2], voffB[2];
; #pragma unroll
;     for (int i = 0; i < 2; ++i) { int R, C; stage_rc(tid * 16 + i * 8192, R, C); const int Rb = Epi::PERM ? ((R & ~31) + perm32(R & 31)) : R;
;         voffA[i] = (unsigned)(R * g.lda + C) * 2u; voffB[i] = (unsigned)(Rb * g.ldb + C) * 2u; }
;     const size_t kstep = (size_t)(BK * 2);
;     const size_t hstepA = (size_t)HALF * g.lda * 2, hstepB = (size_t)HALF * g.ldb * 2;
;     const size_t tstepA = 2 * hstepA, tstepB = 2 * hstepB;
;     const unsigned ldsw = (unsigned)wid * 1024u;
;     const int aoff = lds_byte(wr * 64 + fr, fq * 8), boff = lds_byte(wc * 32 + fr, fq * 8);
;     ...
;     Unit cur, nxt; int ui = 0;
;     if (!S.next(0, cur)) return;
;     f32x4 acc[2][2][4][2];
; #pragma unroll
;     for (int a = 0; a < 2; ++a)
; #pragma unroll
;         for (int b = 0; b < 2; ++b)
; #pragma unroll
;             for (int m = 0; m < 4; ++m)
; #pragma unroll
;                 for (int n = 0; n < 2; ++n) acc[a][b][m][n] = (f32x4){0.f, 0.f, 0.f, 0.f};
;     bf16x8 At[4][2], B0[2][2], B1[2][2];
;     const char* cA = PG8_UA(cur); const char* cB = PG8_UB(cur);
;     PG8_STAGE(PG8_SB(0, 0), cB, voffB); PG8_STAGE(PG8_SB(0, 1), cB + hstepB, voffB); PG8_STAGE(PG8_SA(0, 0), cA, voffA); PG8_STAGE(PG8_SA(0, 1), cA + hstepA, voffA);
;     if (wr == 1) PG8_BAR;
;     PG8_WAIT_V(2); PG8_BAR;
;     PG8_STAGE(PG8_SB(1, 0), cB + kstep, voffB); PG8_STAGE(PG8_SA(1, 0), cA + kstep, voffA); PG8_STAGE(PG8_SB(1, 1), cB + hstepB + kstep, voffB);
.LBB0_1428:
	v_bfe_i32 v4, v1, 27, 1
	v_lshlrev_b32_e32 v2, 4, v1
	v_lshrrev_b32_e32 v4, 22, v4
	v_add_u32_e32 v4, v2, v4
	v_and_b32_e32 v4, 0xfffffc00, v4
	v_sub_u32_e32 v4, v2, v4
	s_waitcnt lgkmcnt(0)
	v_ashrrev_i32_e32 v3, 31, v1
	v_lshrrev_b32_e32 v5, 4, v4
	v_lshrrev_b32_e32 v3, 26, v3
	v_bitop3_b32 v5, v5, v4, 32 bitop3:0x6c
	v_ashrrev_i32_e32 v4, 31, v4
	v_add_u32_e32 v3, v1, v3
	v_lshrrev_b32_e32 v4, 26, v4
	v_ashrrev_i32_e32 v3, 6, v3
	v_add_u32_e32 v4, v5, v4
	v_lshlrev_b32_e32 v6, 3, v3
	v_ashrrev_i32_e32 v4, 6, v4
	v_and_b32_e32 v6, -16, v6
	v_mul_i32_i24_e32 v7, 64, v4
	v_add_u32_e32 v6, v4, v6
	v_sub_u32_e32 v5, v5, v7
	v_mov_b32_e32 v9, 1
	v_lshlrev_b32_e32 v3, 5, v3
	v_ashrrev_i16_sdwa v5, v9, sext(v5) dst_sel:DWORD dst_unused:UNUSED_PAD src0_sel:DWORD src1_sel:BYTE_0
	v_lshlrev_b32_e32 v7, 1, v6
	v_lshrrev_b32_e32 v8, 2, v6
	v_and_b32_e32 v4, 3, v4
	s_mov_b32 s7, 0x7fffe0
	v_and_b32_e32 v3, 32, v3
	v_bfe_i32 v5, v5, 0, 16
	v_and_b32_e32 v7, 24, v7
	v_and_b32_e32 v8, 4, v8
	v_and_or_b32 v4, v6, s7, v4
	v_or3_b32 v4, v4, v8, v7
	v_add_lshl_u32 v3, v3, v5, 1
	v_add_u32_e32 v2, 0x2000, v2
	v_lshl_add_u32 v130, v6, 9, v3
	v_lshl_add_u32 v132, v4, 9, v3
	v_ashrrev_i32_e32 v3, 31, v2
	v_lshrrev_b32_e32 v3, 22, v3
	v_add_u32_e32 v3, v2, v3
	v_readlane_b32 s8, v255, 42
	v_ashrrev_i32_e32 v3, 10, v3
	v_readlane_b32 s9, v255, 43
	v_mul_i32_i24_e32 v4, 0x400, v3
	s_lshl_b64 s[8:9], s[8:9], 22
	v_readlane_b32 s5, v254, 11
	v_sub_u32_e32 v2, v2, v4
	s_add_u32 s42, s5, s8
	v_readlane_b32 s5, v254, 12
	v_lshrrev_b32_e32 v4, 4, v2
	s_addc_u32 s52, s5, s9
	v_bitop3_b32 v2, v4, v2, 32 bitop3:0x6c
	s_add_u32 s53, s88, 0x4800000
	v_ashrrev_i32_e32 v5, 31, v2
	s_addc_u32 s62, s89, 0
	v_lshrrev_b32_e32 v5, 26, v5
	s_add_i32 s4, s6, s4
	s_bfe_u32 s100, s4, 0x10005
	s_bfe_u32 s101, s4, 0x30002
	s_andn2_b32 s4, s4, 0x3c
	s_lshl_b32 s100, s100, 2
	s_lshl_b32 s101, s101, 3
	s_or_b32 s4, s4, s100
	s_or_b32 s4, s4, s101
	v_lshlrev_b32_e32 v4, 3, v3
	v_add_u32_e32 v5, v2, v5
	s_ashr_i32 s6, s4, 31
	v_and_b32_e32 v4, -16, v4
	v_ashrrev_i32_e32 v6, 6, v5
	s_lshr_b32 s6, s6, 26
	v_add_u32_e32 v4, v6, v4
	v_and_b32_e32 v6, 3, v6
	s_add_i32 s6, s4, s6
	v_and_or_b32 v6, v4, s7, v6
	s_ashr_i32 s7, s6, 6
	s_and_b32 s6, s6, 0xffc0
	s_sub_i32 s6, s4, s6
	s_bfe_i32 s4, s6, 0x80000
	s_bfe_u32 s4, s4, 0x3000c
	s_add_i32 s9, s6, s4
	s_bfe_i32 s4, s9, 0x80000
	s_and_b32 s9, s9, 0xf8
	s_sub_i32 s6, s6, s9
	s_lshl_b32 s7, s7, 3
	s_sext_i32_i16 s4, s4
	s_sext_i32_i8 s6, s6
	s_ashr_i32 s5, s3, 6
	s_lshr_b32 s4, s4, 3
	s_add_i32 s10, s7, s6
	s_ashr_i32 s11, s10, 31
	s_bfe_i64 s[12:13], s[4:5], 0x100000
	v_and_b32_e32 v5, 0xc0, v5
	s_ashr_i32 s8, s3, 8
	s_lshl_b32 s63, s5, 10
	s_lshl_b64 s[6:7], s[10:11], 17
	s_lshl_b64 s[12:13], s[12:13], 17
	v_sub_u32_e32 v2, v2, v5
	s_add_u32 s12, s53, s12
	v_lshlrev_b32_e32 v3, 5, v3
	v_ashrrev_i16_sdwa v2, v9, sext(v2) dst_sel:DWORD dst_unused:UNUSED_PAD src0_sel:DWORD src1_sel:BYTE_0
	v_lshlrev_b32_e32 v5, 1, v4
	v_lshrrev_b32_e32 v7, 2, v4
	s_addc_u32 s13, s62, s13
	s_add_i32 s11, s63, 0
	v_and_b32_e32 v3, 32, v3
	v_bfe_i32 v2, v2, 0, 16
	v_and_b32_e32 v5, 24, v5
	v_and_b32_e32 v7, 4, v7
	s_add_i32 m0, s11, 0x10000
	v_or3_b32 v5, v6, v7, v5
	v_add_lshl_u32 v2, v3, v2, 1
	global_load_lds_dwordx4 v132, s[12:13]
	s_add_i32 m0, s11, 0x12000
	v_lshl_add_u32 v136, v5, 9, v2
	s_add_u32 s14, s12, 0x10000
	global_load_lds_dwordx4 v136, s[12:13]
	s_addc_u32 s15, s13, 0
	s_add_i32 m0, s11, 0x14000
	v_lshl_add_u32 v134, v4, 9, v2
	global_load_lds_dwordx4 v132, s[14:15]
	s_add_i32 m0, s11, 0x16000
	s_add_u32 s20, s42, s6
	s_addc_u32 s21, s52, s7
	s_add_i32 s64, s11, 0x2000
	global_load_lds_dwordx4 v136, s[14:15]
	s_mov_b32 m0, s11
	s_add_u32 s6, s20, 0x10000
	global_load_lds_dwordx4 v130, s[20:21]
	s_mov_b32 m0, s64
	s_addc_u32 s7, s21, 0
	s_add_i32 s65, s11, 0x4000
	global_load_lds_dwordx4 v134, s[20:21]
	s_mov_b32 m0, s65
	s_add_i32 s70, s11, 0x6000
	global_load_lds_dwordx4 v130, s[6:7]
	s_mov_b32 m0, s70
	s_cmp_eq_u32 s8, 1
	global_load_lds_dwordx4 v134, s[6:7]
	s_cselect_b64 s[6:7], -1, 0
	s_cmp_lg_u32 s8, 1
	s_cbranch_scc1 .LBB0_1430
	s_barrier

;     __device__ bool next(int i, Unit& u) const {
;         const long L = (long)i * G + c; if (L >= nwg) return false;
;         int wgid = (int)L; { const int q = nwg / NXCD, r = nwg % NXCD, xcd = wgid % NXCD, off = wgid / NXCD; wgid = (xcd < r ? xcd * (q + 1) : r * (q + 1) + (xcd - r) * q) + off; }
;         const int nig = WGM * nN, gid = wgid / nig, fm = gid * WGM, gsz = (nM - fm) < WGM ? (nM - fm) : WGM;
;         u.pm = fm + ((wgid % nig) % gsz); u.pn = (wgid % nig) / gsz; return true;
;     }
.LBB0_1438:
	s_ashr_i32 s3, s3, 3
	s_add_i32 s3, s17, s3
	s_bfe_u32 s100, s3, 0x10005
	s_bfe_u32 s101, s3, 0x30002
	s_andn2_b32 s3, s3, 0x3c
	s_lshl_b32 s100, s100, 2
	s_lshl_b32 s101, s101, 3
	s_or_b32 s3, s3, s100
	s_or_b32 s3, s3, s101
	s_ashr_i32 s14, s3, 31
	s_lshr_b32 s14, s14, 26
	s_add_i32 s14, s3, s14
	s_ashr_i32 s15, s14, 6
	s_lshl_b32 s15, s15, 3
	s_sub_i32 s16, 32, s15
	s_min_i32 s17, s16, 8
	s_abs_i32 s16, s17
	v_cvt_f32_u32_e32 v2, s16
	s_sub_i32 s19, 0, s16
	s_andn2_b32 s14, s14, 63
	s_sub_i32 s3, s3, s14
	v_rcp_iflag_f32_e32 v2, v2
	s_abs_i32 s14, s3
	s_xor_b32 s18, s3, s17
	s_ashr_i32 s18, s18, 31
	v_mul_f32_e32 v2, 0x4f7ffffe, v2
	v_cvt_u32_f32_e32 v2, v2
	s_nop 0
	v_readfirstlane_b32 s22, v2
	s_mul_i32 s19, s19, s22
	s_mul_hi_u32 s19, s22, s19
	s_add_i32 s22, s22, s19
	s_mul_hi_u32 s19, s14, s22
	s_mul_i32 s22, s19, s16
	s_sub_i32 s14, s14, s22
	s_add_i32 s23, s19, 1
	s_sub_i32 s22, s14, s16
	s_cmp_ge_u32 s14, s16
	s_cselect_b32 s19, s23, s19
	s_cselect_b32 s14, s22, s14
	s_add_i32 s22, s19, 1
	s_cmp_ge_u32 s14, s16
	s_cselect_b32 s14, s22, s19
	s_xor_b32 s14, s14, s18
	s_sub_i32 s16, s14, s18
	s_mul_i32 s14, s16, s17
	s_sub_i32 s3, s3, s14
	s_add_i32 s18, s15, s3

;     __device__ bool next(int i, Unit& u) const {
;         const long L = (long)i * G + c; if (L >= nwg) return false;
;         int wgid = (int)L; { const int q = nwg / NXCD, r = nwg % NXCD, xcd = wgid % NXCD, off = wgid / NXCD; wgid = (xcd < r ? xcd * (q + 1) : r * (q + 1) + (xcd - r) * q) + off; }
;         const int nig = WGM * nN, gid = wgid / nig, fm = gid * WGM, gsz = (nM - fm) < WGM ? (nM - fm) : WGM;
;         u.pm = fm + ((wgid % nig) % gsz); u.pn = (wgid % nig) / gsz; return true;
;     }
.LBB0_2021:
	s_ashr_i32 s1, s1, 3
	s_add_i32 s1, s8, s1
	s_bfe_u32 s100, s1, 0x10005
	s_bfe_u32 s101, s1, 0x30002
	s_andn2_b32 s1, s1, 0x3c
	s_lshl_b32 s100, s100, 2
	s_lshl_b32 s101, s101, 3
	s_or_b32 s1, s1, s100
	s_or_b32 s1, s1, s101
	s_ashr_i32 s3, s1, 31
	s_lshr_b32 s3, s3, 26
	s_add_i32 s3, s1, s3
	s_ashr_i32 s6, s3, 6
	s_and_b32 s3, s3, 0xffc0
	s_sub_i32 s1, s1, s3
	s_bfe_i32 s3, s1, 0x80000
	s_bfe_u32 s3, s3, 0x3000c
	s_add_i32 s3, s1, s3
	s_bfe_i32 s7, s3, 0x80000
	s_and_b32 s3, s3, 0xf8
	s_sub_i32 s1, s1, s3
	s_lshl_b32 s6, s6, 3
	s_sext_i32_i16 s7, s7
	s_sext_i32_i8 s1, s1
	s_add_i32 s22, s6, s1
	s_ashr_i32 s6, s7, 3

;     __device__ bool next(int i, Unit& u) const {
;         const long L = (long)i * G + c; if (L >= nwg) return false;
;         int wgid = (int)L; { const int q = nwg / NXCD, r = nwg % NXCD, xcd = wgid % NXCD, off = wgid / NXCD; wgid = (xcd < r ? xcd * (q + 1) : r * (q + 1) + (xcd - r) * q) + off; }
;         const int nig = WGM * nN, gid = wgid / nig, fm = gid * WGM, gsz = (nM - fm) < WGM ? (nM - fm) : WGM;
;         u.pm = fm + ((wgid % nig) % gsz); u.pn = (wgid % nig) / gsz; return true;
;     }
.LBB0_2033:
	s_ashr_i32 s1, s1, 3
	s_add_i32 s1, s7, s1
	s_bfe_u32 s100, s1, 0x10005
	s_bfe_u32 s101, s1, 0x30002
	s_andn2_b32 s1, s1, 0x3c
	s_lshl_b32 s100, s100, 2
	s_lshl_b32 s101, s101, 3
	s_or_b32 s1, s1, s100
	s_or_b32 s1, s1, s101
	s_ashr_i32 s3, s1, 31
	s_lshr_b32 s3, s3, 26
	s_add_i32 s3, s1, s3
	s_ashr_i32 s7, s3, 6
	s_lshl_b32 s7, s7, 3
	s_sub_i32 s12, 32, s7
	s_min_i32 s13, s12, 8
	s_abs_i32 s12, s13
	v_cvt_f32_u32_e32 v2, s12
	s_sub_i32 s15, 0, s12
	s_andn2_b32 s3, s3, 63
	s_sub_i32 s1, s1, s3
	v_rcp_iflag_f32_e32 v2, v2
	s_abs_i32 s3, s1
	s_xor_b32 s14, s1, s13
	s_ashr_i32 s14, s14, 31
	v_mul_f32_e32 v2, 0x4f7ffffe, v2
	v_cvt_u32_f32_e32 v2, v2
	s_nop 0
	v_readfirstlane_b32 s16, v2
	s_mul_i32 s15, s15, s16
	s_mul_hi_u32 s15, s16, s15
	s_add_i32 s16, s16, s15
	s_mul_hi_u32 s15, s3, s16
	s_mul_i32 s16, s15, s12
	s_sub_i32 s3, s3, s16
	s_add_i32 s17, s15, 1
	s_sub_i32 s16, s3, s12
	s_cmp_ge_u32 s3, s12
	s_cselect_b32 s15, s17, s15
	s_cselect_b32 s3, s16, s3
	s_add_i32 s16, s15, 1
	s_cmp_ge_u32 s3, s12
	s_cselect_b32 s3, s16, s15
	s_xor_b32 s3, s3, s14
	s_sub_i32 s12, s3, s14
	s_mul_i32 s3, s12, s13
	s_sub_i32 s1, s1, s3
	s_add_i32 s16, s7, s1

; #define PG8_BAR __builtin_amdgcn_s_barrier()
;     __device__ bool next(int i, Unit& u) const {
;         const long L = (long)i * G + c; if (L >= nwg) return false;
;         int wgid = (int)L; { const int q = nwg / NXCD, r = nwg % NXCD, xcd = wgid % NXCD, off = wgid / NXCD; wgid = (xcd < r ? xcd * (q + 1) : r * (q + 1) + (xcd - r) * q) + off; }
;         const int nig = WGM * nN, gid = wgid / nig, fm = gid * WGM, gsz = (nM - fm) < WGM ? (nM - fm) : WGM;
;         u.pm = fm + ((wgid % nig) % gsz); u.pn = (wgid % nig) / gsz; return true;
;     }
; template <class Epi>
; __device__ __forceinline__ void gemm_phase(LAS unsigned char* lds, const Gemm g, const StaticOrder& S, const Epi& E) {
;     const int tid = launder(threadIdx.x), wid = __builtin_amdgcn_readfirstlane(tid >> 6), lane = tid & 63, wr = wid >> 2, wc = wid & 3, fr = lane & 15, fq = lane >> 4;
;     const int K = g.K, nt = K / BK;
;     unsigned voffA[2], voffB[2];
; #pragma unroll
;     for (int i = 0; i < 2; ++i) { int R, C; stage_rc(tid * 16 + i * 8192, R, C); const int Rb = Epi::PERM ? ((R & ~31) + perm32(R & 31)) : R;
;         voffA[i] = (unsigned)(R * g.lda + C) * 2u; voffB[i] = (unsigned)(Rb * g.ldb + C) * 2u; }
;     const size_t kstep = (size_t)(BK * 2);
;     const size_t hstepA = (size_t)HALF * g.lda * 2, hstepB = (size_t)HALF * g.ldb * 2;
;     const size_t tstepA = 2 * hstepA, tstepB = 2 * hstepB;
;     const unsigned ldsw = (unsigned)wid * 1024u;
;     const int aoff = lds_byte(wr * 64 + fr, fq * 8), boff = lds_byte(wc * 32 + fr, fq * 8);
;     ...
;     Unit cur, nxt; int ui = 0;
;     if (!S.next(0, cur)) return;
;     f32x4 acc[2][2][4][2];
; #pragma unroll
;     for (int a = 0; a < 2; ++a)
; #pragma unroll
;         for (int b = 0; b < 2; ++b)
; #pragma unroll
;             for (int m = 0; m < 4; ++m)
; #pragma unroll
;                 for (int n = 0; n < 2; ++n) acc[a][b][m][n] = (f32x4){0.f, 0.f, 0.f, 0.f};
;     bf16x8 At[4][2], B0[2][2], B1[2][2];
;     const char* cA = PG8_UA(cur); const char* cB = PG8_UB(cur);
;     PG8_STAGE(PG8_SB(0, 0), cB, voffB); PG8_STAGE(PG8_SB(0, 1), cB + hstepB, voffB); PG8_STAGE(PG8_SA(0, 0), cA, voffA); PG8_STAGE(PG8_SA(0, 1), cA + hstepA, voffA);
;     if (wr == 1) PG8_BAR;
;     PG8_WAIT_V(2); PG8_BAR;
;     PG8_STAGE(PG8_SB(1, 0), cB + kstep, voffB); PG8_STAGE(PG8_SA(1, 0), cA + kstep, voffA); PG8_STAGE(PG8_SB(1, 1), cB + hstepB + kstep, voffB);
.LBB0_2118:
	s_waitcnt lgkmcnt(0)
	v_ashrrev_i32_e32 v3, 31, v1
	v_lshrrev_b32_e32 v3, 26, v3
	v_add_u32_e32 v3, v1, v3
	v_ashrrev_i32_e32 v10, 6, v3
	v_bfe_i32 v3, v1, 27, 1
	v_lshlrev_b32_e32 v2, 4, v1
	v_lshrrev_b32_e32 v3, 22, v3
	v_add_u32_e32 v3, v2, v3
	v_and_b32_e32 v3, 0xfffffc00, v3
	v_sub_u32_e32 v3, v2, v3
	v_lshrrev_b32_e32 v4, 4, v3
	v_bitop3_b32 v4, v4, v3, 32 bitop3:0x6c
	v_ashrrev_i32_e32 v3, 31, v3
	v_lshrrev_b32_e32 v3, 26, v3
	v_add_u32_e32 v3, v4, v3
	v_ashrrev_i32_e32 v11, 6, v3
	v_lshlrev_b32_e32 v5, 3, v10
	v_mul_i32_i24_e32 v6, 64, v11
	v_and_b32_e32 v5, -16, v5
	v_sub_u32_e32 v4, v4, v6
	v_mov_b32_e32 v8, 1
	v_add_u32_e32 v3, v11, v5
	v_lshlrev_b32_e32 v5, 5, v10
	v_ashrrev_i16_sdwa v4, v8, sext(v4) dst_sel:DWORD dst_unused:UNUSED_PAD src0_sel:DWORD src1_sel:BYTE_0
	v_and_b32_e32 v5, 32, v5
	v_bfe_i32 v12, v4, 0, 16
	v_and_b32_e32 v7, 3, v11
	s_mov_b32 s1, 0xfffe0
	v_add_lshl_u32 v5, v5, v12, 1
	v_add_u32_e32 v2, 0x2000, v2
	v_lshlrev_b32_e32 v4, 1, v3
	v_lshrrev_b32_e32 v6, 2, v3
	v_and_or_b32 v7, v3, s1, v7
	v_lshl_add_u32 v130, v3, 12, v5
	v_ashrrev_i32_e32 v3, 31, v2
	v_lshrrev_b32_e32 v3, 22, v3
	v_add_u32_e32 v3, v2, v3
	v_ashrrev_i32_e32 v13, 10, v3
	v_mul_i32_i24_e32 v3, 0x400, v13
	v_sub_u32_e32 v2, v2, v3
	v_and_b32_e32 v4, 24, v4
	v_and_b32_e32 v6, 4, v6
	v_lshrrev_b32_e32 v3, 4, v2
	v_or3_b32 v4, v7, v6, v4
	v_bitop3_b32 v2, v3, v2, 32 bitop3:0x6c
	v_lshl_add_u32 v132, v4, 12, v5
	v_ashrrev_i32_e32 v4, 31, v2
	v_lshrrev_b32_e32 v4, 26, v4
	v_lshlrev_b32_e32 v3, 3, v13
	v_add_u32_e32 v4, v2, v4
	v_and_b32_e32 v3, -16, v3
	v_ashrrev_i32_e32 v14, 6, v4
	v_add_u32_e32 v3, v14, v3
	v_and_b32_e32 v6, 3, v14
	s_add_i32 s0, s4, s0
	s_bfe_u32 s100, s0, 0x10007
	s_bfe_u32 s101, s0, 0x50002
	s_andn2_b32 s0, s0, 0xfc
	s_lshl_b32 s100, s100, 2
	s_lshl_b32 s101, s101, 3
	s_or_b32 s0, s0, s100
	s_or_b32 s0, s0, s101
	v_and_or_b32 v6, v3, s1, v6
	s_ashr_i32 s1, s0, 31
	s_lshr_b32 s1, s1, 24
	s_add_i32 s1, s0, s1
	s_ashr_i32 s4, s1, 8
	s_and_b32 s1, s1, 0xff00
	s_sub_i32 s0, s0, s1
	s_sext_i32_i16 s1, s0
	s_bfe_u32 s1, s1, 0x3001c
	s_add_i32 s1, s0, s1
	s_lshl_b32 s7, s4, 3
	s_sext_i32_i16 s4, s1
	s_and_b32 s1, s1, 0xfff8
	s_sub_i32 s0, s0, s1
	s_sext_i32_i16 s0, s0
	s_ashr_i32 s5, s3, 8
	s_lshr_b32 s4, s4, 3
	s_add_i32 s18, s7, s0
	v_and_b32_e32 v4, 0xc0, v4
	s_ashr_i32 s6, s3, 6
	s_ashr_i32 s19, s18, 31
	s_bfe_i64 s[8:9], s[4:5], 0x100000
	v_sub_u32_e32 v2, v2, v4
	s_lshl_b32 s27, s6, 10
	s_lshl_b64 s[0:1], s[18:19], 20
	s_lshl_b64 s[8:9], s[8:9], 20
	v_ashrrev_i16_sdwa v2, v8, sext(v2) dst_sel:DWORD dst_unused:UNUSED_PAD src0_sel:DWORD src1_sel:BYTE_0
	s_add_u32 s22, s88, s8
	v_lshlrev_b32_e32 v5, 5, v13
	v_bfe_i32 v15, v2, 0, 16
	v_lshlrev_b32_e32 v2, 1, v3
	v_lshrrev_b32_e32 v4, 2, v3
	s_addc_u32 s23, s89, s9
	s_add_i32 s19, s27, 0
	v_and_b32_e32 v5, 32, v5
	v_and_b32_e32 v2, 24, v2
	v_and_b32_e32 v4, 4, v4
	s_add_i32 m0, s19, 0x10000
	v_or3_b32 v2, v6, v4, v2
	v_add_lshl_u32 v4, v5, v15, 1
	global_load_lds_dwordx4 v132, s[22:23]
	s_add_i32 m0, s19, 0x12000
	v_lshl_add_u32 v136, v2, 12, v4
	s_add_u32 s8, s22, 0x80000
	global_load_lds_dwordx4 v136, s[22:23]
	s_addc_u32 s9, s23, 0
	s_add_i32 m0, s19, 0x14000
	v_lshl_add_u32 v134, v3, 12, v4
	global_load_lds_dwordx4 v132, s[8:9]
	s_add_i32 m0, s19, 0x16000
	s_add_u32 s20, s54, s0
	s_addc_u32 s21, s55, s1
	s_add_i32 s28, s19, 0x2000
	global_load_lds_dwordx4 v136, s[8:9]
	s_mov_b32 m0, s19
	s_add_u32 s0, s20, 0x80000
	global_load_lds_dwordx4 v130, s[20:21]
	s_mov_b32 m0, s28
	s_addc_u32 s1, s21, 0
	s_add_i32 s29, s19, 0x4000
	global_load_lds_dwordx4 v134, s[20:21]
	s_mov_b32 m0, s29
	s_add_i32 s30, s19, 0x6000
	global_load_lds_dwordx4 v130, s[0:1]
	s_mov_b32 m0, s30
	v_mov_b32_e32 v133, v0
	global_load_lds_dwordx4 v134, s[0:1]
	v_mov_b32_e32 v137, v0
	v_mov_b32_e32 v131, v0
	v_mov_b32_e32 v135, v0
	s_cmp_eq_u32 s5, 1
	v_lshl_add_u64 v[8:9], s[22:23], 0, v[132:133]
	v_lshl_add_u64 v[6:7], s[22:23], 0, v[136:137]
	v_lshl_add_u64 v[2:3], s[20:21], 0, v[130:131]
	s_cselect_b64 s[0:1], -1, 0
	s_cmp_lg_u32 s5, 1
	v_lshl_add_u64 v[4:5], s[20:21], 0, v[134:135]
	s_cbranch_scc1 .LBB0_2120
	s_barrier

;     __device__ bool next(int i, Unit& u) const {
;         const long L = (long)i * G + c; if (L >= nwg) return false;
;         int wgid = (int)L; { const int q = nwg / NXCD, r = nwg % NXCD, xcd = wgid % NXCD, off = wgid / NXCD; wgid = (xcd < r ? xcd * (q + 1) : r * (q + 1) + (xcd - r) * q) + off; }
;         const int nig = WGM * nN, gid = wgid / nig, fm = gid * WGM, gsz = (nM - fm) < WGM ? (nM - fm) : WGM;
;         u.pm = fm + ((wgid % nig) % gsz); u.pn = (wgid % nig) / gsz; return true;
;     }
.LBB0_2128:
	s_ashr_i32 s3, s3, 3
	s_add_i32 s3, s11, s3
	s_bfe_u32 s100, s3, 0x10007
	s_bfe_u32 s101, s3, 0x50002
	s_andn2_b32 s3, s3, 0xfc
	s_lshl_b32 s100, s100, 2
	s_lshl_b32 s101, s101, 3
	s_or_b32 s3, s3, s100
	s_or_b32 s3, s3, s101
	s_ashr_i32 s8, s3, 31
	s_lshr_b32 s8, s8, 24
	s_add_i32 s8, s3, s8
	s_ashr_i32 s9, s8, 8
	s_lshl_b32 s9, s9, 3
	s_sub_i32 s10, 32, s9
	s_min_i32 s10, s10, 8
	s_abs_i32 s11, s10
	v_cvt_f32_u32_e32 v2, s11
	s_sub_i32 s13, 0, s11
	s_and_b32 s8, s8, 0xffffff00
	s_sub_i32 s3, s3, s8
	v_rcp_iflag_f32_e32 v2, v2
	s_abs_i32 s8, s3
	s_xor_b32 s12, s3, s10
	s_ashr_i32 s12, s12, 31
	v_mul_f32_e32 v2, 0x4f7ffffe, v2
	v_cvt_u32_f32_e32 v2, v2
	s_nop 0
	v_readfirstlane_b32 s14, v2
	s_mul_i32 s13, s13, s14
	s_mul_hi_u32 s13, s14, s13
	s_add_i32 s14, s14, s13
	s_mul_hi_u32 s13, s8, s14
	s_mul_i32 s14, s13, s11
	s_sub_i32 s8, s8, s14
	s_add_i32 s15, s13, 1
	s_sub_i32 s14, s8, s11
	s_cmp_ge_u32 s8, s11
	s_cselect_b32 s13, s15, s13
	s_cselect_b32 s8, s14, s8
	s_add_i32 s14, s13, 1
	s_cmp_ge_u32 s8, s11
	s_cselect_b32 s8, s14, s13
	s_xor_b32 s8, s8, s12
	s_sub_i32 s8, s8, s12
	s_mul_i32 s10, s8, s10
	s_sub_i32 s3, s3, s10
	s_add_i32 s10, s9, s3

; #define PG8_BAR __builtin_amdgcn_s_barrier()
;     __device__ bool next(int i, Unit& u) const {
;         const long L = (long)i * G + c; if (L >= nwg) return false;
;         int wgid = (int)L; { const int q = nwg / NXCD, r = nwg % NXCD, xcd = wgid % NXCD, off = wgid / NXCD; wgid = (xcd < r ? xcd * (q + 1) : r * (q + 1) + (xcd - r) * q) + off; }
;         const int nig = WGM * nN, gid = wgid / nig, fm = gid * WGM, gsz = (nM - fm) < WGM ? (nM - fm) : WGM;
;         u.pm = fm + ((wgid % nig) % gsz); u.pn = (wgid % nig) / gsz; return true;
;     }
; template <class Epi>
; __device__ __forceinline__ void gemm_phase(LAS unsigned char* lds, const Gemm g, const StaticOrder& S, const Epi& E) {
;     const int tid = launder(threadIdx.x), wid = __builtin_amdgcn_readfirstlane(tid >> 6), lane = tid & 63, wr = wid >> 2, wc = wid & 3, fr = lane & 15, fq = lane >> 4;
;     const int K = g.K, nt = K / BK;
;     unsigned voffA[2], voffB[2];
; #pragma unroll
;     for (int i = 0; i < 2; ++i) { int R, C; stage_rc(tid * 16 + i * 8192, R, C); const int Rb = Epi::PERM ? ((R & ~31) + perm32(R & 31)) : R;
;         voffA[i] = (unsigned)(R * g.lda + C) * 2u; voffB[i] = (unsigned)(Rb * g.ldb + C) * 2u; }
;     const size_t kstep = (size_t)(BK * 2);
;     const size_t hstepA = (size_t)HALF * g.lda * 2, hstepB = (size_t)HALF * g.ldb * 2;
;     const size_t tstepA = 2 * hstepA, tstepB = 2 * hstepB;
;     const unsigned ldsw = (unsigned)wid * 1024u;
;     const int aoff = lds_byte(wr * 64 + fr, fq * 8), boff = lds_byte(wc * 32 + fr, fq * 8);
;     ...
;     Unit cur, nxt; int ui = 0;
;     if (!S.next(0, cur)) return;
;     f32x4 acc[2][2][4][2];
; #pragma unroll
;     for (int a = 0; a < 2; ++a)
; #pragma unroll
;         for (int b = 0; b < 2; ++b)
; #pragma unroll
;             for (int m = 0; m < 4; ++m)
; #pragma unroll
;                 for (int n = 0; n < 2; ++n) acc[a][b][m][n] = (f32x4){0.f, 0.f, 0.f, 0.f};
;     bf16x8 At[4][2], B0[2][2], B1[2][2];
;     const char* cA = PG8_UA(cur); const char* cB = PG8_UB(cur);
;     PG8_STAGE(PG8_SB(0, 0), cB, voffB); PG8_STAGE(PG8_SB(0, 1), cB + hstepB, voffB); PG8_STAGE(PG8_SA(0, 0), cA, voffA); PG8_STAGE(PG8_SA(0, 1), cA + hstepA, voffA);
;     if (wr == 1) PG8_BAR;
;     PG8_WAIT_V(2); PG8_BAR;
;     PG8_STAGE(PG8_SB(1, 0), cB + kstep, voffB); PG8_STAGE(PG8_SA(1, 0), cA + kstep, voffA); PG8_STAGE(PG8_SB(1, 1), cB + hstepB + kstep, voffB);
.LBB0_2143:
	v_bfe_i32 v4, v1, 27, 1
	v_lshlrev_b32_e32 v2, 4, v1
	v_lshrrev_b32_e32 v4, 22, v4
	v_add_u32_e32 v4, v2, v4
	v_and_b32_e32 v4, 0xfffffc00, v4
	v_sub_u32_e32 v4, v2, v4
	s_waitcnt lgkmcnt(0)
	v_ashrrev_i32_e32 v3, 31, v1
	v_lshrrev_b32_e32 v5, 4, v4
	v_lshrrev_b32_e32 v3, 26, v3
	v_bitop3_b32 v5, v5, v4, 32 bitop3:0x6c
	v_ashrrev_i32_e32 v4, 31, v4
	v_add_u32_e32 v3, v1, v3
	v_lshrrev_b32_e32 v4, 26, v4
	v_readlane_b32 s8, v255, 42
	v_ashrrev_i32_e32 v3, 6, v3
	v_add_u32_e32 v4, v5, v4
	v_readlane_b32 s9, v255, 43
	v_lshlrev_b32_e32 v6, 3, v3
	v_ashrrev_i32_e32 v4, 6, v4
	s_lshl_b64 s[8:9], s[8:9], 22
	v_readlane_b32 s1, v254, 11
	v_and_b32_e32 v6, -16, v6
	v_mul_i32_i24_e32 v7, 64, v4
	s_add_u32 s42, s1, s8
	v_readlane_b32 s1, v254, 12
	v_add_u32_e32 v6, v4, v6
	v_sub_u32_e32 v5, v5, v7
	v_mov_b32_e32 v9, 1
	s_addc_u32 s52, s1, s9
	v_lshlrev_b32_e32 v3, 5, v3
	v_ashrrev_i16_sdwa v5, v9, sext(v5) dst_sel:DWORD dst_unused:UNUSED_PAD src0_sel:DWORD src1_sel:BYTE_0
	v_lshlrev_b32_e32 v7, 1, v6
	v_lshrrev_b32_e32 v8, 2, v6
	v_and_b32_e32 v4, 3, v4
	s_mov_b32 s1, 0x7fffe0
	v_and_b32_e32 v3, 32, v3
	v_bfe_i32 v5, v5, 0, 16
	v_and_b32_e32 v7, 24, v7
	v_and_b32_e32 v8, 4, v8
	v_and_or_b32 v4, v6, s1, v4
	v_or3_b32 v4, v4, v8, v7
	v_add_lshl_u32 v3, v3, v5, 1
	v_add_u32_e32 v2, 0x2000, v2
	v_lshl_add_u32 v130, v6, 9, v3
	v_lshl_add_u32 v132, v4, 9, v3
	v_ashrrev_i32_e32 v3, 31, v2
	v_lshrrev_b32_e32 v3, 22, v3
	v_add_u32_e32 v3, v2, v3
	v_ashrrev_i32_e32 v3, 10, v3
	v_mul_i32_i24_e32 v4, 0x400, v3
	v_sub_u32_e32 v2, v2, v4
	v_lshrrev_b32_e32 v4, 4, v2
	v_bitop3_b32 v2, v4, v2, 32 bitop3:0x6c
	v_ashrrev_i32_e32 v5, 31, v2
	v_lshrrev_b32_e32 v5, 26, v5
	v_lshlrev_b32_e32 v4, 3, v3
	v_add_u32_e32 v5, v2, v5
	s_add_u32 s53, s88, 0x4800000
	v_and_b32_e32 v4, -16, v4
	v_ashrrev_i32_e32 v6, 6, v5
	s_addc_u32 s62, s89, 0
	v_add_u32_e32 v4, v6, v4
	v_and_b32_e32 v6, 3, v6
	s_add_i32 s0, s6, s0
	s_bfe_u32 s100, s0, 0x10005
	s_bfe_u32 s101, s0, 0x30002
	s_andn2_b32 s0, s0, 0x3c
	s_lshl_b32 s100, s100, 2
	s_lshl_b32 s101, s101, 3
	s_or_b32 s0, s0, s100
	s_or_b32 s0, s0, s101
	v_and_or_b32 v6, v4, s1, v6
	s_ashr_i32 s1, s0, 31
	s_lshr_b32 s1, s1, 26
	s_add_i32 s1, s0, s1
	s_ashr_i32 s6, s1, 6
	s_and_b32 s1, s1, 0xffc0
	s_sub_i32 s0, s0, s1
	s_bfe_i32 s1, s0, 0x80000
	s_bfe_u32 s1, s1, 0x3000c
	s_add_i32 s1, s0, s1
	s_lshl_b32 s9, s6, 3
	s_bfe_i32 s6, s1, 0x80000
	s_and_b32 s1, s1, 0xf8
	s_sub_i32 s0, s0, s1
	s_sext_i32_i16 s6, s6
	s_sext_i32_i8 s0, s0
	s_ashr_i32 s7, s3, 6
	s_lshr_b32 s6, s6, 3
	s_add_i32 s10, s9, s0
	s_ashr_i32 s11, s10, 31
	s_bfe_i64 s[12:13], s[6:7], 0x100000
	v_and_b32_e32 v5, 0xc0, v5
	s_ashr_i32 s8, s3, 8
	s_lshl_b32 s63, s7, 10
	s_lshl_b64 s[0:1], s[10:11], 17
	s_lshl_b64 s[12:13], s[12:13], 17
	v_sub_u32_e32 v2, v2, v5
	s_add_u32 s12, s53, s12
	v_lshlrev_b32_e32 v3, 5, v3
	v_ashrrev_i16_sdwa v2, v9, sext(v2) dst_sel:DWORD dst_unused:UNUSED_PAD src0_sel:DWORD src1_sel:BYTE_0
	v_lshlrev_b32_e32 v5, 1, v4
	v_lshrrev_b32_e32 v7, 2, v4
	s_addc_u32 s13, s62, s13
	s_add_i32 s11, s63, 0
	v_and_b32_e32 v3, 32, v3
	v_bfe_i32 v2, v2, 0, 16
	v_and_b32_e32 v5, 24, v5
	v_and_b32_e32 v7, 4, v7
	s_add_i32 m0, s11, 0x10000
	v_or3_b32 v5, v6, v7, v5
	v_add_lshl_u32 v2, v3, v2, 1
	global_load_lds_dwordx4 v132, s[12:13]
	s_add_i32 m0, s11, 0x12000
	v_lshl_add_u32 v136, v5, 9, v2
	s_add_u32 s14, s12, 0x10000
	global_load_lds_dwordx4 v136, s[12:13]
	s_addc_u32 s15, s13, 0
	s_add_i32 m0, s11, 0x14000
	v_lshl_add_u32 v134, v4, 9, v2
	global_load_lds_dwordx4 v132, s[14:15]
	s_add_i32 m0, s11, 0x16000
	s_add_u32 s20, s42, s0
	s_addc_u32 s21, s52, s1
	s_add_i32 s64, s11, 0x2000
	global_load_lds_dwordx4 v136, s[14:15]
	s_mov_b32 m0, s11
	s_add_u32 s0, s20, 0x10000
	global_load_lds_dwordx4 v130, s[20:21]
	s_mov_b32 m0, s64
	s_addc_u32 s1, s21, 0
	s_add_i32 s65, s11, 0x4000
	global_load_lds_dwordx4 v134, s[20:21]
	s_mov_b32 m0, s65
	s_add_i32 s70, s11, 0x6000
	global_load_lds_dwordx4 v130, s[0:1]
	s_mov_b32 m0, s70
	s_cmp_eq_u32 s8, 1
	global_load_lds_dwordx4 v134, s[0:1]
	s_cselect_b64 s[0:1], -1, 0
	s_cmp_lg_u32 s8, 1
	s_cbranch_scc1 .LBB0_2145
	s_barrier

;     __device__ bool next(int i, Unit& u) const {
;         const long L = (long)i * G + c; if (L >= nwg) return false;
;         int wgid = (int)L; { const int q = nwg / NXCD, r = nwg % NXCD, xcd = wgid % NXCD, off = wgid / NXCD; wgid = (xcd < r ? xcd * (q + 1) : r * (q + 1) + (xcd - r) * q) + off; }
;         const int nig = WGM * nN, gid = wgid / nig, fm = gid * WGM, gsz = (nM - fm) < WGM ? (nM - fm) : WGM;
;         u.pm = fm + ((wgid % nig) % gsz); u.pn = (wgid % nig) / gsz; return true;
;     }
.LBB0_2219:
	s_ashr_i32 s0, s8, 3
	s_add_i32 s0, s10, s0
	s_bfe_u32 s100, s0, 0x10005
	s_bfe_u32 s101, s0, 0x30002
	s_andn2_b32 s0, s0, 0x3c
	s_lshl_b32 s100, s100, 2
	s_lshl_b32 s101, s101, 3
	s_or_b32 s0, s0, s100
	s_or_b32 s0, s0, s101
	s_ashr_i32 s1, s0, 31
	s_lshr_b32 s1, s1, 26
	s_add_i32 s1, s0, s1
	s_ashr_i32 s8, s1, 6
	s_and_b32 s1, s1, 0xffc0
	s_sub_i32 s0, s0, s1
	s_bfe_i32 s1, s0, 0x80000
	s_bfe_u32 s1, s1, 0x3000c
	s_add_i32 s1, s0, s1
	s_bfe_i32 s9, s1, 0x80000
	s_and_b32 s1, s1, 0xf8
	s_sub_i32 s0, s0, s1
	s_lshl_b32 s8, s8, 3
	s_sext_i32_i16 s9, s9
	s_sext_i32_i8 s0, s0
	s_add_i32 s8, s8, s0
	s_ashr_i32 s0, s9, 3

;     __device__ bool next(int i, Unit& u) const {
;         const long L = (long)i * G + c; if (L >= nwg) return false;
;         int wgid = (int)L; { const int q = nwg / NXCD, r = nwg % NXCD, xcd = wgid % NXCD, off = wgid / NXCD; wgid = (xcd < r ? xcd * (q + 1) : r * (q + 1) + (xcd - r) * q) + off; }
;         const int nig = WGM * nN, gid = wgid / nig, fm = gid * WGM, gsz = (nM - fm) < WGM ? (nM - fm) : WGM;
;         u.pm = fm + ((wgid % nig) % gsz); u.pn = (wgid % nig) / gsz; return true;
;     }
.LBB0_2231:
	s_ashr_i32 s1, s1, 3
	s_add_i32 s1, s9, s1
	s_bfe_u32 s100, s1, 0x10005
	s_bfe_u32 s101, s1, 0x30002
	s_andn2_b32 s1, s1, 0x3c
	s_lshl_b32 s100, s100, 2
	s_lshl_b32 s101, s101, 3
	s_or_b32 s1, s1, s100
	s_or_b32 s1, s1, s101
	s_ashr_i32 s3, s1, 31
	s_lshr_b32 s3, s3, 26
	s_add_i32 s3, s1, s3
	s_ashr_i32 s9, s3, 6
	s_lshl_b32 s9, s9, 3
	s_sub_i32 s14, 32, s9
	s_min_i32 s14, s14, 8
	s_abs_i32 s15, s14
	v_cvt_f32_u32_e32 v2, s15
	s_sub_i32 s17, 0, s15
	s_andn2_b32 s3, s3, 63
	s_sub_i32 s1, s1, s3
	v_rcp_iflag_f32_e32 v2, v2
	s_abs_i32 s3, s1
	s_xor_b32 s16, s1, s14
	s_ashr_i32 s16, s16, 31
	v_mul_f32_e32 v2, 0x4f7ffffe, v2
	v_cvt_u32_f32_e32 v2, v2
	s_nop 0
	v_readfirstlane_b32 s18, v2
	s_mul_i32 s17, s17, s18
	s_mul_hi_u32 s17, s18, s17
	s_add_i32 s18, s18, s17
	s_mul_hi_u32 s17, s3, s18
	s_mul_i32 s18, s17, s15
	s_sub_i32 s3, s3, s18
	s_add_i32 s19, s17, 1
	s_sub_i32 s18, s3, s15
	s_cmp_ge_u32 s3, s15
	s_cselect_b32 s17, s19, s17
	s_cselect_b32 s3, s18, s3
	s_add_i32 s18, s17, 1
	s_cmp_ge_u32 s3, s15
	s_cselect_b32 s3, s18, s17
	s_xor_b32 s3, s3, s16
	s_sub_i32 s16, s3, s16
	s_mul_i32 s3, s16, s14
	s_sub_i32 s1, s1, s3
	s_add_i32 s18, s9, s1

;     __device__ bool next(int i, Unit& u) const {
;         const long L = (long)i * G + c; if (L >= nwg) return false;
;         int wgid = (int)L; { const int q = nwg / NXCD, r = nwg % NXCD, xcd = wgid % NXCD, off = wgid / NXCD; wgid = (xcd < r ? xcd * (q + 1) : r * (q + 1) + (xcd - r) * q) + off; }
;         const int nig = WGM * nN, gid = wgid / nig, fm = gid * WGM, gsz = (nM - fm) < WGM ? (nM - fm) : WGM;
;         u.pm = fm + ((wgid % nig) % gsz); u.pn = (wgid % nig) / gsz; return true;
;     }
.LBB0_2318:
	s_ashr_i32 s0, s4, 3
	s_add_i32 s0, s8, s0
	s_bfe_u32 s100, s0, 0x10005
	s_bfe_u32 s101, s0, 0x30002
	s_andn2_b32 s0, s0, 0x3c
	s_lshl_b32 s100, s100, 2
	s_lshl_b32 s101, s101, 3
	s_or_b32 s0, s0, s100
	s_or_b32 s0, s0, s101
	s_ashr_i32 s1, s0, 31
	s_lshr_b32 s1, s1, 26
	s_add_i32 s1, s0, s1
	s_ashr_i32 s4, s1, 6
	s_and_b32 s1, s1, 0xffc0
	s_sub_i32 s0, s0, s1
	s_bfe_i32 s1, s0, 0x80000
	s_bfe_u32 s1, s1, 0x3000c
	s_add_i32 s1, s0, s1
	s_bfe_i32 s5, s1, 0x80000
	s_and_b32 s1, s1, 0xf8
	s_sub_i32 s0, s0, s1
	s_lshl_b32 s4, s4, 3
	s_sext_i32_i16 s5, s5
	s_sext_i32_i8 s0, s0
	s_add_i32 s8, s4, s0
	s_ashr_i32 s0, s5, 3

; #define PG8_STAGE(bufoff, gbase, voff) do { _Pragma("unroll") for (int _i = 0; _i < 2; ++_i) \
;         __builtin_amdgcn_global_load_lds((const unsigned*)((const char*)(gbase) + (voff)[_i]), (LAS unsigned*)(lds + (bufoff) + ldsw + _i * 8192), 16, 0, 0); } while (0)
;     __device__ bool next(int i, Unit& u) const {
;         const long L = (long)i * G + c; if (L >= nwg) return false;
;         int wgid = (int)L; { const int q = nwg / NXCD, r = nwg % NXCD, xcd = wgid % NXCD, off = wgid / NXCD; wgid = (xcd < r ? xcd * (q + 1) : r * (q + 1) + (xcd - r) * q) + off; }
;         const int nig = WGM * nN, gid = wgid / nig, fm = gid * WGM, gsz = (nM - fm) < WGM ? (nM - fm) : WGM;
;         u.pm = fm + ((wgid % nig) % gsz); u.pn = (wgid % nig) / gsz; return true;
; template <class Epi>
; __device__ __forceinline__ void gemm_phase(LAS unsigned char* lds, const Gemm g, const StaticOrder& S, const Epi& E) {
;     ...
;     for (int i = 0; i < 2; ++i) { int R, C; stage_rc(tid * 16 + i * 8192, R, C); const int Rb = Epi::PERM ? ((R & ~31) + perm32(R & 31)) : R;
;         voffA[i] = (unsigned)(R * g.lda + C) * 2u; voffB[i] = (unsigned)(Rb * g.ldb + C) * 2u; }
;     const size_t kstep = (size_t)(BK * 2);
;     const size_t hstepA = (size_t)HALF * g.lda * 2, hstepB = (size_t)HALF * g.ldb * 2;
;     const size_t tstepA = 2 * hstepA, tstepB = 2 * hstepB;
;     const unsigned ldsw = (unsigned)wid * 1024u;
;     const int aoff = lds_byte(wr * 64 + fr, fq * 8), boff = lds_byte(wc * 32 + fr, fq * 8);
;     ...
;     Unit cur, nxt; int ui = 0;
;     if (!S.next(0, cur)) return;
;     f32x4 acc[2][2][4][2];
; #pragma unroll
;     for (int a = 0; a < 2; ++a)
; #pragma unroll
;         for (int b = 0; b < 2; ++b)
; #pragma unroll
;             for (int m = 0; m < 4; ++m)
; #pragma unroll
;                 for (int n = 0; n < 2; ++n) acc[a][b][m][n] = (f32x4){0.f, 0.f, 0.f, 0.f};
;     bf16x8 At[4][2], B0[2][2], B1[2][2];
;     const char* cA = PG8_UA(cur); const char* cB = PG8_UB(cur);
;     PG8_STAGE(PG8_SB(0, 0), cB, voffB); PG8_STAGE(PG8_SB(0, 1), cB + hstepB, voffB); PG8_STAGE(PG8_SA(0, 0), cA, voffA); PG8_STAGE(PG8_SA(0, 1), cA + hstepA, voffA);
;     if (wr == 1) PG8_BAR;
;     PG8_WAIT_V(2); PG8_BAR;
;     PG8_STAGE(PG8_SB(1, 0), cB + kstep, voffB); PG8_STAGE(PG8_SA(1, 0), cA + kstep, voffA); PG8_STAGE(PG8_SB(1, 1), cB + hstepB + kstep, voffB);
;     PG8_WAIT_V(6); PG8_BAR;
.LBB0_2364:
	s_waitcnt lgkmcnt(0)
	v_ashrrev_i32_e32 v3, 31, v1
	v_lshrrev_b32_e32 v3, 26, v3
	v_add_u32_e32 v3, v1, v3
	v_ashrrev_i32_e32 v10, 6, v3
	v_bfe_i32 v3, v1, 27, 1
	v_lshlrev_b32_e32 v2, 4, v1
	v_lshrrev_b32_e32 v3, 22, v3
	v_add_u32_e32 v3, v2, v3
	v_and_b32_e32 v3, 0xfffffc00, v3
	v_sub_u32_e32 v3, v2, v3
	v_lshrrev_b32_e32 v4, 4, v3
	v_bitop3_b32 v4, v4, v3, 32 bitop3:0x6c
	v_ashrrev_i32_e32 v3, 31, v3
	v_lshrrev_b32_e32 v3, 26, v3
	v_add_u32_e32 v3, v4, v3
	v_ashrrev_i32_e32 v11, 6, v3
	v_lshlrev_b32_e32 v5, 3, v10
	v_mul_i32_i24_e32 v6, 64, v11
	v_and_b32_e32 v5, -16, v5
	v_sub_u32_e32 v4, v4, v6
	v_mov_b32_e32 v8, 1
	v_add_u32_e32 v3, v11, v5
	v_lshlrev_b32_e32 v5, 5, v10
	v_ashrrev_i16_sdwa v4, v8, sext(v4) dst_sel:DWORD dst_unused:UNUSED_PAD src0_sel:DWORD src1_sel:BYTE_0
	v_and_b32_e32 v5, 32, v5
	v_bfe_i32 v12, v4, 0, 16
	v_and_b32_e32 v7, 3, v11
	s_mov_b32 s1, 0xfffe0
	v_add_lshl_u32 v5, v5, v12, 1
	v_add_u32_e32 v2, 0x2000, v2
	v_lshlrev_b32_e32 v4, 1, v3
	v_lshrrev_b32_e32 v6, 2, v3
	v_and_or_b32 v7, v3, s1, v7
	v_lshl_add_u32 v154, v3, 12, v5
	v_ashrrev_i32_e32 v3, 31, v2
	v_lshrrev_b32_e32 v3, 22, v3
	v_add_u32_e32 v3, v2, v3
	v_ashrrev_i32_e32 v13, 10, v3
	v_mul_i32_i24_e32 v3, 0x400, v13
	v_sub_u32_e32 v2, v2, v3
	v_and_b32_e32 v4, 24, v4
	v_and_b32_e32 v6, 4, v6
	v_lshrrev_b32_e32 v3, 4, v2
	v_or3_b32 v4, v7, v6, v4
	v_bitop3_b32 v2, v3, v2, 32 bitop3:0x6c
	v_lshl_add_u32 v156, v4, 12, v5
	v_ashrrev_i32_e32 v4, 31, v2
	v_lshrrev_b32_e32 v4, 26, v4
	v_lshlrev_b32_e32 v3, 3, v13
	v_add_u32_e32 v4, v2, v4
	v_and_b32_e32 v3, -16, v3
	v_ashrrev_i32_e32 v14, 6, v4
	v_add_u32_e32 v3, v14, v3
	v_and_b32_e32 v6, 3, v14
	s_add_i32 s0, s6, s0
	s_bfe_u32 s100, s0, 0x10005
	s_bfe_u32 s101, s0, 0x30002
	s_andn2_b32 s0, s0, 0x3c
	s_lshl_b32 s100, s100, 2
	s_lshl_b32 s101, s101, 3
	s_or_b32 s0, s0, s100
	s_or_b32 s0, s0, s101
	v_and_or_b32 v6, v3, s1, v6
	s_ashr_i32 s1, s0, 31
	s_lshr_b32 s1, s1, 26
	s_add_i32 s1, s0, s1
	s_ashr_i32 s6, s1, 6
	s_and_b32 s1, s1, 0xffc0
	s_sub_i32 s0, s0, s1
	s_bfe_i32 s1, s0, 0x80000
	s_bfe_u32 s1, s1, 0x3000c
	s_add_i32 s1, s0, s1
	s_lshl_b32 s8, s6, 3
	s_bfe_i32 s6, s1, 0x80000
	s_and_b32 s1, s1, 0xf8
	s_sub_i32 s0, s0, s1
	s_sext_i32_i16 s6, s6
	s_sext_i32_i8 s0, s0
	s_ashr_i32 s7, s3, 8
	s_lshr_b32 s6, s6, 3
	s_add_i32 s8, s8, s0
	v_and_b32_e32 v4, 0xc0, v4
	s_ashr_i32 s10, s3, 6
	s_ashr_i32 s9, s8, 31
	s_bfe_i64 s[12:13], s[6:7], 0x100000
	v_sub_u32_e32 v2, v2, v4
	s_lshl_b32 s27, s10, 10
	s_lshl_b64 s[0:1], s[8:9], 20
	s_lshl_b64 s[12:13], s[12:13], 20
	v_ashrrev_i16_sdwa v2, v8, sext(v2) dst_sel:DWORD dst_unused:UNUSED_PAD src0_sel:DWORD src1_sel:BYTE_0
	s_add_u32 s24, s28, s12
	v_lshlrev_b32_e32 v5, 5, v13
	v_bfe_i32 v15, v2, 0, 16
	v_lshlrev_b32_e32 v2, 1, v3
	v_lshrrev_b32_e32 v4, 2, v3
	s_addc_u32 s25, s29, s13
	s_add_i32 s30, s27, 0
	v_and_b32_e32 v5, 32, v5
	v_and_b32_e32 v2, 24, v2
	v_and_b32_e32 v4, 4, v4
	s_add_i32 m0, s30, 0x10000
	v_or3_b32 v2, v6, v4, v2
	v_add_lshl_u32 v4, v5, v15, 1
	global_load_lds_dwordx4 v156, s[24:25]
	s_add_i32 m0, s30, 0x12000
	v_lshl_add_u32 v160, v2, 12, v4
	s_add_u32 s12, s24, 0x80000
	global_load_lds_dwordx4 v160, s[24:25]
	s_addc_u32 s13, s25, 0
	s_add_i32 m0, s30, 0x14000
	v_lshl_add_u32 v158, v3, 12, v4
	global_load_lds_dwordx4 v156, s[12:13]
	s_add_i32 m0, s30, 0x16000
	s_add_u32 s14, s60, s0
	s_addc_u32 s15, s61, s1
	s_add_i32 s31, s30, 0x2000
	global_load_lds_dwordx4 v160, s[12:13]
	s_mov_b32 m0, s30
	s_add_u32 s0, s14, 0x80000
	global_load_lds_dwordx4 v154, s[14:15]
	s_mov_b32 m0, s31
	s_addc_u32 s1, s15, 0
	s_add_i32 s34, s30, 0x4000
	global_load_lds_dwordx4 v158, s[14:15]
	s_mov_b32 m0, s34
	s_add_i32 s35, s30, 0x6000
	global_load_lds_dwordx4 v154, s[0:1]
	s_mov_b32 m0, s35
	v_mov_b32_e32 v157, v0
	global_load_lds_dwordx4 v158, s[0:1]
	v_mov_b32_e32 v161, v0
	v_mov_b32_e32 v155, v0
	v_mov_b32_e32 v159, v0
	s_cmp_eq_u32 s7, 1
	v_lshl_add_u64 v[8:9], s[24:25], 0, v[156:157]
	v_lshl_add_u64 v[6:7], s[24:25], 0, v[160:161]
	v_lshl_add_u64 v[2:3], s[14:15], 0, v[154:155]
	s_cselect_b64 s[0:1], -1, 0
	s_cmp_lg_u32 s7, 1
	v_lshl_add_u64 v[4:5], s[14:15], 0, v[158:159]
	s_cbranch_scc1 .LBB0_2366
	s_barrier

;     __device__ bool next(int i, Unit& u) const {
;         const long L = (long)i * G + c; if (L >= nwg) return false;
;         int wgid = (int)L; { const int q = nwg / NXCD, r = nwg % NXCD, xcd = wgid % NXCD, off = wgid / NXCD; wgid = (xcd < r ? xcd * (q + 1) : r * (q + 1) + (xcd - r) * q) + off; }
;         const int nig = WGM * nN, gid = wgid / nig, fm = gid * WGM, gsz = (nM - fm) < WGM ? (nM - fm) : WGM;
;         u.pm = fm + ((wgid % nig) % gsz); u.pn = (wgid % nig) / gsz; return true;
.LBB0_2374:
	s_ashr_i32 s3, s3, 3
	s_add_i32 s3, s16, s3
	s_bfe_u32 s100, s3, 0x10005
	s_bfe_u32 s101, s3, 0x30002
	s_andn2_b32 s3, s3, 0x3c
	s_lshl_b32 s100, s100, 2
	s_lshl_b32 s101, s101, 3
	s_or_b32 s3, s3, s100
	s_or_b32 s3, s3, s101
	s_ashr_i32 s9, s3, 31
	s_lshr_b32 s9, s9, 26
	s_add_i32 s9, s3, s9
	s_ashr_i32 s12, s9, 6
	s_lshl_b32 s13, s12, 3
	s_sub_i32 s12, 32, s13
	s_min_i32 s16, s12, 8
	s_abs_i32 s12, s16
	v_cvt_f32_u32_e32 v2, s12
	s_sub_i32 s18, 0, s12
	s_andn2_b32 s9, s9, 63
	s_sub_i32 s3, s3, s9
	v_rcp_iflag_f32_e32 v2, v2
	s_abs_i32 s9, s3
	s_xor_b32 s17, s3, s16
	s_ashr_i32 s17, s17, 31
	v_mul_f32_e32 v2, 0x4f7ffffe, v2
	v_cvt_u32_f32_e32 v2, v2
	s_nop 0
	v_readfirstlane_b32 s19, v2
	s_mul_i32 s18, s18, s19
	s_mul_hi_u32 s18, s19, s18
	s_add_i32 s19, s19, s18
	s_mul_hi_u32 s18, s9, s19
	s_mul_i32 s19, s18, s12
	s_sub_i32 s9, s9, s19
	s_add_i32 s20, s18, 1
	s_sub_i32 s19, s9, s12
	s_cmp_ge_u32 s9, s12
	s_cselect_b32 s18, s20, s18
	s_cselect_b32 s9, s19, s9
	s_add_i32 s19, s18, 1
	s_cmp_ge_u32 s9, s12
	s_cselect_b32 s9, s19, s18
	s_xor_b32 s9, s9, s17
	s_sub_i32 s12, s9, s17
	s_mul_i32 s9, s12, s16
	s_sub_i32 s3, s3, s9
	s_add_i32 s16, s13, s3

; __global__ void __launch_bounds__(NTHR, 2) mk_fwd(Args args) {
	.amdhsa_kernel _Z6mk_fwd4Args
		.amdhsa_group_segment_fixed_size 0
		.amdhsa_private_segment_fixed_size 0
		.amdhsa_kernarg_size 752
		.amdhsa_user_sgpr_count 2
		.amdhsa_user_sgpr_dispatch_ptr 0
		.amdhsa_user_sgpr_queue_ptr 0
		.amdhsa_user_sgpr_kernarg_segment_ptr 1
		.amdhsa_user_sgpr_dispatch_id 0
		.amdhsa_user_sgpr_kernarg_preload_length 0
		.amdhsa_user_sgpr_kernarg_preload_offset 0
		.amdhsa_user_sgpr_private_segment_size 0
		.amdhsa_uses_dynamic_stack 0
		.amdhsa_enable_private_segment 0
		.amdhsa_system_sgpr_workgroup_id_x 1
		.amdhsa_system_sgpr_workgroup_id_y 0
		.amdhsa_system_sgpr_workgroup_id_z 0
		.amdhsa_system_sgpr_workgroup_info 0
		.amdhsa_system_vgpr_workitem_id 2
		.amdhsa_next_free_vgpr 256
		.amdhsa_next_free_sgpr 102
		.amdhsa_accum_offset 256
		.amdhsa_reserve_vcc 1
		.amdhsa_float_round_mode_32 0
		.amdhsa_float_round_mode_16_64 0
		.amdhsa_float_denorm_mode_32 3
		.amdhsa_float_denorm_mode_16_64 3
		.amdhsa_dx10_clamp 1
		.amdhsa_ieee_mode 1
		.amdhsa_fp16_overflow 0
		.amdhsa_tg_split 0
		.amdhsa_exception_fp_ieee_invalid_op 0
		.amdhsa_exception_fp_denorm_src 0
		.amdhsa_exception_fp_ieee_div_zero 0
		.amdhsa_exception_fp_ieee_overflow 0
		.amdhsa_exception_fp_ieee_underflow 0
		.amdhsa_exception_fp_ieee_inexact 0
		.amdhsa_exception_int_div_zero 0
	.end_amdhsa_kernel

; __global__ void __launch_bounds__(NTHR, 2) mk_fwd(Args args) {
amdhsa.kernels:
  - .agpr_count:     0
    .args:
      - .offset:         0
        .size:           496
        .value_kind:     by_value
      - .offset:         496
        .size:           4
        .value_kind:     hidden_block_count_x
      - .offset:         500
        .size:           4
        .value_kind:     hidden_block_count_y
      - .offset:         504
        .size:           4
        .value_kind:     hidden_block_count_z
      - .offset:         508
        .size:           2
        .value_kind:     hidden_group_size_x
      - .offset:         510
        .size:           2
        .value_kind:     hidden_group_size_y
      - .offset:         512
        .size:           2
        .value_kind:     hidden_group_size_z
      - .offset:         514
        .size:           2
        .value_kind:     hidden_remainder_x
      - .offset:         516
        .size:           2
        .value_kind:     hidden_remainder_y
      - .offset:         518
        .size:           2
        .value_kind:     hidden_remainder_z
      - .offset:         536
        .size:           8
        .value_kind:     hidden_global_offset_x
      - .offset:         544
        .size:           8
        .value_kind:     hidden_global_offset_y
      - .offset:         552
        .size:           8
        .value_kind:     hidden_global_offset_z
      - .offset:         560
        .size:           2
        .value_kind:     hidden_grid_dims
      - .offset:         584
        .size:           8
        .value_kind:     hidden_multigrid_sync_arg
      - .offset:         616
        .size:           4
        .value_kind:     hidden_dynamic_lds_size
    .group_segment_fixed_size: 0
    .kernarg_segment_align: 8
    .kernarg_segment_size: 752
    .language:       OpenCL C
    .language_version:
      - 2
      - 0
    .max_flat_workgroup_size: 512
    .name:           _Z6mk_fwd4Args
    .private_segment_fixed_size: 0
    .sgpr_count:     108
    .sgpr_spill_count: 112
    .symbol:         _Z6mk_fwd4Args.kd
    .uniform_work_group_size: 1
    .uses_dynamic_stack: false
    .vgpr_count:     256
    .vgpr_spill_count: 0
    .wavefront_size: 64
